# GEMM main loops: per-segment s_setprio 1/0 toggling removed (all four GEMM phases run at default priority)
# speedup vs baseline: 1.0024x; 1.0024x over previous
.LBB0_188:
	ds_read_b128 v[130:133], v249
	ds_read_b128 v[134:137], v249 offset:1024
	ds_read_b128 v[138:141], v249 offset:2048
	ds_read_b128 v[142:145], v249 offset:3072
	ds_read_b128 v[146:149], v250
	ds_read_b128 v[150:153], v250 offset:1024
	ds_read_b128 v[154:157], v250 offset:2048
	ds_read_b128 v[158:161], v250 offset:3072
	s_add_u32 s66, s64, 0xfff80080
	s_addc_u32 s67, s65, -1
	s_cmp_eq_u32 vcc_hi, 28
	s_cselect_b32 s69, s7, s67
	s_cselect_b32 s68, s55, s66
	s_cselect_b32 s67, s57, vcc_lo
	s_cselect_b32 s66, s63, s97
	v_lshl_add_u64 v[216:217], s[64:65], 0, v[214:215]
	s_add_i32 m0, s78, 0xc000
	ds_read_b128 v[162:165], v251
	ds_read_b128 v[166:169], v251 offset:1024
	ds_read_b128 v[170:173], v251 offset:2048
	ds_read_b128 v[174:177], v251 offset:3072
	ds_read_b128 v[178:181], v251 offset:4096
	ds_read_b128 v[182:185], v251 offset:5120
	ds_read_b128 v[186:189], v251 offset:6144
	ds_read_b128 v[190:193], v251 offset:7168
	global_load_lds_dwordx4 v[216:217], off
	v_lshl_add_u64 v[216:217], s[64:65], 0, v[212:213]
	s_add_i32 m0, s78, 0xe000
	s_nop 0
	global_load_lds_dwordx4 v[216:217], off
	s_waitcnt vmcnt(8)
	s_waitcnt lgkmcnt(0)
	s_barrier
	s_waitcnt lgkmcnt(0)
	v_mfma_f32_16x16x32_bf16 v[126:129], v[130:133], v[162:165], v[126:129]
	v_mfma_f32_16x16x32_bf16 v[122:125], v[138:141], v[162:165], v[122:125]
	v_mfma_f32_16x16x32_bf16 v[110:113], v[130:133], v[170:173], v[110:113]
	v_mfma_f32_16x16x32_bf16 v[106:109], v[138:141], v[170:173], v[106:109]
	v_mfma_f32_16x16x32_bf16 v[94:97], v[130:133], v[178:181], v[94:97]
	v_mfma_f32_16x16x32_bf16 v[90:93], v[138:141], v[178:181], v[90:93]
	v_mfma_f32_16x16x32_bf16 v[78:81], v[130:133], v[186:189], v[78:81]
	v_mfma_f32_16x16x32_bf16 v[74:77], v[138:141], v[186:189], v[74:77]
	v_mfma_f32_16x16x32_bf16 v[126:129], v[134:137], v[166:169], v[126:129]
	v_mfma_f32_16x16x32_bf16 v[122:125], v[142:145], v[166:169], v[122:125]
	v_mfma_f32_16x16x32_bf16 v[110:113], v[134:137], v[174:177], v[110:113]
	v_mfma_f32_16x16x32_bf16 v[106:109], v[142:145], v[174:177], v[106:109]
	v_mfma_f32_16x16x32_bf16 v[94:97], v[134:137], v[182:185], v[94:97]
	v_mfma_f32_16x16x32_bf16 v[90:93], v[142:145], v[182:185], v[90:93]
	v_mfma_f32_16x16x32_bf16 v[78:81], v[134:137], v[190:193], v[78:81]
	v_mfma_f32_16x16x32_bf16 v[74:77], v[142:145], v[190:193], v[74:77]
	v_mfma_f32_16x16x32_bf16 v[118:121], v[146:149], v[162:165], v[118:121]
	v_mfma_f32_16x16x32_bf16 v[114:117], v[154:157], v[162:165], v[114:117]
	v_mfma_f32_16x16x32_bf16 v[102:105], v[146:149], v[170:173], v[102:105]
	v_mfma_f32_16x16x32_bf16 v[98:101], v[154:157], v[170:173], v[98:101]
	v_mfma_f32_16x16x32_bf16 v[86:89], v[146:149], v[178:181], v[86:89]
	v_mfma_f32_16x16x32_bf16 v[82:85], v[154:157], v[178:181], v[82:85]
	v_mfma_f32_16x16x32_bf16 v[70:73], v[146:149], v[186:189], v[70:73]
	v_mfma_f32_16x16x32_bf16 v[66:69], v[154:157], v[186:189], v[66:69]
	v_mfma_f32_16x16x32_bf16 v[118:121], v[150:153], v[166:169], v[118:121]
	v_mfma_f32_16x16x32_bf16 v[114:117], v[158:161], v[166:169], v[114:117]
	v_mfma_f32_16x16x32_bf16 v[102:105], v[150:153], v[174:177], v[102:105]
	v_mfma_f32_16x16x32_bf16 v[98:101], v[158:161], v[174:177], v[98:101]
	v_mfma_f32_16x16x32_bf16 v[86:89], v[150:153], v[182:185], v[86:89]
	v_mfma_f32_16x16x32_bf16 v[82:85], v[158:161], v[182:185], v[82:85]
	v_mfma_f32_16x16x32_bf16 v[70:73], v[150:153], v[190:193], v[70:73]
	v_mfma_f32_16x16x32_bf16 v[66:69], v[158:161], v[190:193], v[66:69]
	s_barrier
	s_add_i32 s70, s89, s77
	v_lshl_add_u64 v[216:217], s[66:67], 0, v[198:199]
	s_mov_b32 m0, s70
	ds_read_b128 v[162:165], v251 offset:16384
	ds_read_b128 v[166:169], v251 offset:17408
	ds_read_b128 v[170:173], v251 offset:18432
	ds_read_b128 v[174:177], v251 offset:19456
	ds_read_b128 v[178:181], v251 offset:20480
	ds_read_b128 v[182:185], v251 offset:21504
	ds_read_b128 v[186:189], v251 offset:22528
	ds_read_b128 v[190:193], v251 offset:23552
	global_load_lds_dwordx4 v[216:217], off
	s_add_i32 m0, s70, 0x2000
	s_add_u32 s70, s66, 0x80000
	v_lshl_add_u64 v[218:219], s[66:67], 0, v[202:203]
	s_addc_u32 s71, s67, 0
	s_add_i32 s72, s90, s77
	global_load_lds_dwordx4 v[218:219], off
	v_lshl_add_u64 v[220:221], s[70:71], 0, v[198:199]
	s_mov_b32 m0, s72
	v_lshl_add_u64 v[222:223], s[68:69], 0, v[200:201]
	global_load_lds_dwordx4 v[220:221], off
	v_lshl_add_u64 v[220:221], s[70:71], 0, v[202:203]
	s_add_i32 m0, s72, 0x2000
	s_nop 0
	global_load_lds_dwordx4 v[220:221], off
	v_lshl_add_u64 v[220:221], s[68:69], 0, v[196:197]
	s_mov_b32 m0, s78
	s_nop 0
	global_load_lds_dwordx4 v[220:221], off
	s_mov_b32 m0, s79
	s_nop 0
	global_load_lds_dwordx4 v[222:223], off
	s_waitcnt vmcnt(8)
	s_waitcnt lgkmcnt(0)
	s_barrier
	s_waitcnt lgkmcnt(0)
	v_mfma_f32_16x16x32_bf16 v[62:65], v[130:133], v[162:165], v[62:65]
	v_mfma_f32_16x16x32_bf16 v[58:61], v[138:141], v[162:165], v[58:61]
	v_mfma_f32_16x16x32_bf16 v[46:49], v[130:133], v[170:173], v[46:49]
	v_mfma_f32_16x16x32_bf16 v[42:45], v[138:141], v[170:173], v[42:45]
	v_mfma_f32_16x16x32_bf16 v[30:33], v[130:133], v[178:181], v[30:33]
	v_mfma_f32_16x16x32_bf16 v[26:29], v[138:141], v[178:181], v[26:29]
	v_mfma_f32_16x16x32_bf16 v[14:17], v[130:133], v[186:189], v[14:17]
	v_mfma_f32_16x16x32_bf16 v[10:13], v[138:141], v[186:189], v[10:13]
	v_mfma_f32_16x16x32_bf16 v[62:65], v[134:137], v[166:169], v[62:65]
	v_mfma_f32_16x16x32_bf16 v[58:61], v[142:145], v[166:169], v[58:61]
	v_mfma_f32_16x16x32_bf16 v[46:49], v[134:137], v[174:177], v[46:49]
	v_mfma_f32_16x16x32_bf16 v[42:45], v[142:145], v[174:177], v[42:45]
	v_mfma_f32_16x16x32_bf16 v[30:33], v[134:137], v[182:185], v[30:33]
	v_mfma_f32_16x16x32_bf16 v[26:29], v[142:145], v[182:185], v[26:29]
	v_mfma_f32_16x16x32_bf16 v[14:17], v[134:137], v[190:193], v[14:17]
	v_mfma_f32_16x16x32_bf16 v[10:13], v[142:145], v[190:193], v[10:13]
	v_mfma_f32_16x16x32_bf16 v[54:57], v[146:149], v[162:165], v[54:57]
	v_mfma_f32_16x16x32_bf16 v[50:53], v[154:157], v[162:165], v[50:53]
	v_mfma_f32_16x16x32_bf16 v[38:41], v[146:149], v[170:173], v[38:41]
	v_mfma_f32_16x16x32_bf16 v[34:37], v[154:157], v[170:173], v[34:37]
	v_mfma_f32_16x16x32_bf16 v[22:25], v[146:149], v[178:181], v[22:25]
	v_mfma_f32_16x16x32_bf16 v[18:21], v[154:157], v[178:181], v[18:21]
	v_mfma_f32_16x16x32_bf16 v[6:9], v[146:149], v[186:189], v[6:9]
	v_mfma_f32_16x16x32_bf16 v[2:5], v[154:157], v[186:189], v[2:5]
	v_mfma_f32_16x16x32_bf16 v[54:57], v[150:153], v[166:169], v[54:57]
	v_mfma_f32_16x16x32_bf16 v[50:53], v[158:161], v[166:169], v[50:53]
	v_mfma_f32_16x16x32_bf16 v[38:41], v[150:153], v[174:177], v[38:41]
	v_mfma_f32_16x16x32_bf16 v[34:37], v[158:161], v[174:177], v[34:37]
	v_mfma_f32_16x16x32_bf16 v[22:25], v[150:153], v[182:185], v[22:25]
	v_mfma_f32_16x16x32_bf16 v[18:21], v[158:161], v[182:185], v[18:21]
	v_mfma_f32_16x16x32_bf16 v[6:9], v[150:153], v[190:193], v[6:9]
	v_mfma_f32_16x16x32_bf16 v[2:5], v[158:161], v[190:193], v[2:5]
	s_barrier
	s_add_i32 s70, 0, 0x18000
	s_add_i32 s71, 0, 0x1c000
	v_add_u32_e32 v142, s70, v248
	v_add_u32_e32 v158, s71, v248
	ds_read_b128 v[130:133], v142
	ds_read_b128 v[134:137], v142 offset:1024
	ds_read_b128 v[138:141], v142 offset:2048
	ds_read_b128 v[142:145], v142 offset:3072
	ds_read_b128 v[146:149], v158
	ds_read_b128 v[150:153], v158 offset:1024
	ds_read_b128 v[154:157], v158 offset:2048
	ds_read_b128 v[158:161], v158 offset:3072
	s_add_u32 s68, s68, 0x80000
	s_addc_u32 s69, s69, 0
	s_mov_b32 m0, s80
	v_lshl_add_u64 v[224:225], s[68:69], 0, v[196:197]
	ds_read_b128 v[162:165], v251 offset:32768
	ds_read_b128 v[166:169], v251 offset:33792
	ds_read_b128 v[170:173], v251 offset:34816
	ds_read_b128 v[174:177], v251 offset:35840
	ds_read_b128 v[178:181], v251 offset:36864
	ds_read_b128 v[182:185], v251 offset:37888
	ds_read_b128 v[186:189], v251 offset:38912
	ds_read_b128 v[190:193], v251 offset:39936
	global_load_lds_dwordx4 v[224:225], off
	v_lshl_add_u64 v[224:225], s[68:69], 0, v[200:201]
	s_mov_b32 m0, s81
	s_nop 0
	global_load_lds_dwordx4 v[224:225], off
	s_waitcnt vmcnt(8)
	s_waitcnt lgkmcnt(0)
	s_barrier
	s_waitcnt lgkmcnt(0)
	v_mfma_f32_16x16x32_bf16 v[126:129], v[130:133], v[162:165], v[126:129]
	v_mfma_f32_16x16x32_bf16 v[122:125], v[138:141], v[162:165], v[122:125]
	v_mfma_f32_16x16x32_bf16 v[110:113], v[130:133], v[170:173], v[110:113]
	v_mfma_f32_16x16x32_bf16 v[106:109], v[138:141], v[170:173], v[106:109]
	v_mfma_f32_16x16x32_bf16 v[94:97], v[130:133], v[178:181], v[94:97]
	v_mfma_f32_16x16x32_bf16 v[90:93], v[138:141], v[178:181], v[90:93]
	v_mfma_f32_16x16x32_bf16 v[78:81], v[130:133], v[186:189], v[78:81]
	v_mfma_f32_16x16x32_bf16 v[74:77], v[138:141], v[186:189], v[74:77]
	v_mfma_f32_16x16x32_bf16 v[126:129], v[134:137], v[166:169], v[126:129]
	v_mfma_f32_16x16x32_bf16 v[122:125], v[142:145], v[166:169], v[122:125]
	v_mfma_f32_16x16x32_bf16 v[110:113], v[134:137], v[174:177], v[110:113]
	v_mfma_f32_16x16x32_bf16 v[106:109], v[142:145], v[174:177], v[106:109]
	v_mfma_f32_16x16x32_bf16 v[94:97], v[134:137], v[182:185], v[94:97]
	v_mfma_f32_16x16x32_bf16 v[90:93], v[142:145], v[182:185], v[90:93]
	v_mfma_f32_16x16x32_bf16 v[78:81], v[134:137], v[190:193], v[78:81]
	v_mfma_f32_16x16x32_bf16 v[74:77], v[142:145], v[190:193], v[74:77]
	v_mfma_f32_16x16x32_bf16 v[118:121], v[146:149], v[162:165], v[118:121]
	v_mfma_f32_16x16x32_bf16 v[114:117], v[154:157], v[162:165], v[114:117]
	v_mfma_f32_16x16x32_bf16 v[102:105], v[146:149], v[170:173], v[102:105]
	v_mfma_f32_16x16x32_bf16 v[98:101], v[154:157], v[170:173], v[98:101]
	v_mfma_f32_16x16x32_bf16 v[86:89], v[146:149], v[178:181], v[86:89]
	v_mfma_f32_16x16x32_bf16 v[82:85], v[154:157], v[178:181], v[82:85]
	v_mfma_f32_16x16x32_bf16 v[70:73], v[146:149], v[186:189], v[70:73]
	v_mfma_f32_16x16x32_bf16 v[66:69], v[154:157], v[186:189], v[66:69]
	v_mfma_f32_16x16x32_bf16 v[118:121], v[150:153], v[166:169], v[118:121]
	v_mfma_f32_16x16x32_bf16 v[114:117], v[158:161], v[166:169], v[114:117]
	v_mfma_f32_16x16x32_bf16 v[102:105], v[150:153], v[174:177], v[102:105]
	v_mfma_f32_16x16x32_bf16 v[98:101], v[158:161], v[174:177], v[98:101]
	v_mfma_f32_16x16x32_bf16 v[86:89], v[150:153], v[182:185], v[86:89]
	v_mfma_f32_16x16x32_bf16 v[82:85], v[158:161], v[182:185], v[82:85]
	v_mfma_f32_16x16x32_bf16 v[70:73], v[150:153], v[190:193], v[70:73]
	v_mfma_f32_16x16x32_bf16 v[66:69], v[158:161], v[190:193], v[66:69]
	s_barrier
	s_add_i32 s68, s70, s77
	v_lshl_add_u64 v[216:217], v[216:217], 0, s[18:19]
	s_mov_b32 m0, s68
	ds_read_b128 v[162:165], v251 offset:49152
	ds_read_b128 v[166:169], v251 offset:50176
	ds_read_b128 v[170:173], v251 offset:51200
	ds_read_b128 v[174:177], v251 offset:52224
	ds_read_b128 v[178:181], v251 offset:53248
	ds_read_b128 v[182:185], v251 offset:54272
	ds_read_b128 v[186:189], v251 offset:55296
	ds_read_b128 v[190:193], v251 offset:56320
	global_load_lds_dwordx4 v[216:217], off
	s_add_i32 m0, s68, 0x2000
	s_add_u32 s66, s66, 0x80080
	v_lshl_add_u64 v[216:217], v[218:219], 0, s[18:19]
	s_addc_u32 s67, s67, 0
	s_add_i32 s68, s71, s77
	global_load_lds_dwordx4 v[216:217], off
	v_lshl_add_u64 v[216:217], s[66:67], 0, v[198:199]
	s_mov_b32 m0, s68
	s_nop 0
	global_load_lds_dwordx4 v[216:217], off
	v_lshl_add_u64 v[216:217], s[66:67], 0, v[202:203]
	s_add_i32 m0, s68, 0x2000
	s_nop 0
	global_load_lds_dwordx4 v[216:217], off
	v_lshl_add_u64 v[216:217], v[220:221], 0, s[18:19]
	s_mov_b32 m0, s86
	s_nop 0
	global_load_lds_dwordx4 v[216:217], off
	v_lshl_add_u64 v[216:217], v[222:223], 0, s[18:19]
	s_mov_b32 m0, s87
	s_nop 0
	global_load_lds_dwordx4 v[216:217], off
	s_waitcnt vmcnt(8)
	s_waitcnt lgkmcnt(0)
	s_barrier
	s_waitcnt lgkmcnt(0)
	v_mfma_f32_16x16x32_bf16 v[62:65], v[130:133], v[162:165], v[62:65]
	v_mfma_f32_16x16x32_bf16 v[58:61], v[138:141], v[162:165], v[58:61]
	v_mfma_f32_16x16x32_bf16 v[46:49], v[130:133], v[170:173], v[46:49]
	v_mfma_f32_16x16x32_bf16 v[42:45], v[138:141], v[170:173], v[42:45]
	v_mfma_f32_16x16x32_bf16 v[30:33], v[130:133], v[178:181], v[30:33]
	v_mfma_f32_16x16x32_bf16 v[26:29], v[138:141], v[178:181], v[26:29]
	v_mfma_f32_16x16x32_bf16 v[14:17], v[130:133], v[186:189], v[14:17]
	v_mfma_f32_16x16x32_bf16 v[10:13], v[138:141], v[186:189], v[10:13]
	v_mfma_f32_16x16x32_bf16 v[62:65], v[134:137], v[166:169], v[62:65]
	v_mfma_f32_16x16x32_bf16 v[58:61], v[142:145], v[166:169], v[58:61]
	v_mfma_f32_16x16x32_bf16 v[46:49], v[134:137], v[174:177], v[46:49]
	v_mfma_f32_16x16x32_bf16 v[42:45], v[142:145], v[174:177], v[42:45]
	v_mfma_f32_16x16x32_bf16 v[30:33], v[134:137], v[182:185], v[30:33]
	v_mfma_f32_16x16x32_bf16 v[26:29], v[142:145], v[182:185], v[26:29]
	v_mfma_f32_16x16x32_bf16 v[14:17], v[134:137], v[190:193], v[14:17]
	v_mfma_f32_16x16x32_bf16 v[10:13], v[142:145], v[190:193], v[10:13]
	v_mfma_f32_16x16x32_bf16 v[54:57], v[146:149], v[162:165], v[54:57]
	v_mfma_f32_16x16x32_bf16 v[50:53], v[154:157], v[162:165], v[50:53]
	v_mfma_f32_16x16x32_bf16 v[38:41], v[146:149], v[170:173], v[38:41]
	v_mfma_f32_16x16x32_bf16 v[34:37], v[154:157], v[170:173], v[34:37]
	v_mfma_f32_16x16x32_bf16 v[22:25], v[146:149], v[178:181], v[22:25]
	v_mfma_f32_16x16x32_bf16 v[18:21], v[154:157], v[178:181], v[18:21]
	v_mfma_f32_16x16x32_bf16 v[6:9], v[146:149], v[186:189], v[6:9]
	v_mfma_f32_16x16x32_bf16 v[2:5], v[154:157], v[186:189], v[2:5]
	v_mfma_f32_16x16x32_bf16 v[54:57], v[150:153], v[166:169], v[54:57]
	v_mfma_f32_16x16x32_bf16 v[50:53], v[158:161], v[166:169], v[50:53]
	v_mfma_f32_16x16x32_bf16 v[38:41], v[150:153], v[174:177], v[38:41]
	v_mfma_f32_16x16x32_bf16 v[34:37], v[158:161], v[174:177], v[34:37]
	v_mfma_f32_16x16x32_bf16 v[22:25], v[150:153], v[182:185], v[22:25]
	v_mfma_f32_16x16x32_bf16 v[18:21], v[158:161], v[182:185], v[18:21]
	v_mfma_f32_16x16x32_bf16 v[6:9], v[150:153], v[190:193], v[6:9]
	v_mfma_f32_16x16x32_bf16 v[2:5], v[158:161], v[190:193], v[2:5]
	s_barrier
	s_add_i32 vcc_hi, vcc_hi, 2
	s_add_u32 s97, s97, 0x100
	s_addc_u32 vcc_lo, vcc_lo, 0
	s_add_u32 s64, s64, 0x100
	s_addc_u32 s65, s65, 0
	s_cmp_gt_u32 vcc_hi, 29
	s_cbranch_scc0 .LBB0_188
	s_and_b64 vcc, exec, s[20:21]
	s_cbranch_vccz .LBB0_191
	s_barrier

.LBB0_482:
	ds_read_b128 v[162:165], v157
	ds_read_b128 v[166:169], v157 offset:1024
	ds_read_b128 v[170:173], v157 offset:2048
	ds_read_b128 v[174:177], v157 offset:3072
	ds_read_b128 v[178:181], v158
	ds_read_b128 v[182:185], v158 offset:1024
	ds_read_b128 v[186:189], v158 offset:2048
	ds_read_b128 v[190:193], v158 offset:3072
	s_add_u32 s16, s12, s14
	s_addc_u32 s17, s13, s15
	s_add_u32 s16, s16, 0x3000100
	s_addc_u32 s17, s17, 0
	s_add_u32 s56, s43, s14
	s_addc_u32 s57, s44, s15
	s_cmpk_eq_i32 s14, 0xf00
	s_cselect_b32 s19, s9, s17
	s_cselect_b32 s18, s8, s16
	s_cselect_b32 s17, s5, s57
	s_cselect_b32 s16, s4, s56
	s_mov_b32 m0, s46
	v_lshl_add_u64 v[226:227], v[140:141], 0, s[14:15]
	ds_read_b128 v[194:197], v159
	ds_read_b128 v[198:201], v159 offset:1024
	ds_read_b128 v[202:205], v159 offset:2048
	ds_read_b128 v[206:209], v159 offset:3072
	ds_read_b128 v[210:213], v159 offset:4096
	ds_read_b128 v[214:217], v159 offset:5120
	ds_read_b128 v[218:221], v159 offset:6144
	ds_read_b128 v[222:225], v159 offset:7168
	global_load_lds_dwordx4 v[226:227], off
	v_lshl_add_u64 v[226:227], v[138:139], 0, s[14:15]
	s_mov_b32 m0, s47
	s_nop 0
	global_load_lds_dwordx4 v[226:227], off
	s_waitcnt vmcnt(8)
	s_waitcnt lgkmcnt(0)
	s_barrier
	s_waitcnt lgkmcnt(0)
	v_mfma_f32_16x16x32_bf16 v[126:129], v[162:165], v[194:197], v[126:129]
	v_mfma_f32_16x16x32_bf16 v[122:125], v[170:173], v[194:197], v[122:125]
	v_mfma_f32_16x16x32_bf16 v[110:113], v[162:165], v[202:205], v[110:113]
	v_mfma_f32_16x16x32_bf16 v[106:109], v[170:173], v[202:205], v[106:109]
	v_mfma_f32_16x16x32_bf16 v[94:97], v[162:165], v[210:213], v[94:97]
	v_mfma_f32_16x16x32_bf16 v[90:93], v[170:173], v[210:213], v[90:93]
	v_mfma_f32_16x16x32_bf16 v[78:81], v[162:165], v[218:221], v[78:81]
	v_mfma_f32_16x16x32_bf16 v[74:77], v[170:173], v[218:221], v[74:77]
	v_mfma_f32_16x16x32_bf16 v[126:129], v[166:169], v[198:201], v[126:129]
	v_mfma_f32_16x16x32_bf16 v[122:125], v[174:177], v[198:201], v[122:125]
	v_mfma_f32_16x16x32_bf16 v[110:113], v[166:169], v[206:209], v[110:113]
	v_mfma_f32_16x16x32_bf16 v[106:109], v[174:177], v[206:209], v[106:109]
	v_mfma_f32_16x16x32_bf16 v[94:97], v[166:169], v[214:217], v[94:97]
	v_mfma_f32_16x16x32_bf16 v[90:93], v[174:177], v[214:217], v[90:93]
	v_mfma_f32_16x16x32_bf16 v[78:81], v[166:169], v[222:225], v[78:81]
	v_mfma_f32_16x16x32_bf16 v[74:77], v[174:177], v[222:225], v[74:77]
	v_mfma_f32_16x16x32_bf16 v[118:121], v[178:181], v[194:197], v[118:121]
	v_mfma_f32_16x16x32_bf16 v[114:117], v[186:189], v[194:197], v[114:117]
	v_mfma_f32_16x16x32_bf16 v[102:105], v[178:181], v[202:205], v[102:105]
	v_mfma_f32_16x16x32_bf16 v[98:101], v[186:189], v[202:205], v[98:101]
	v_mfma_f32_16x16x32_bf16 v[86:89], v[178:181], v[210:213], v[86:89]
	v_mfma_f32_16x16x32_bf16 v[82:85], v[186:189], v[210:213], v[82:85]
	v_mfma_f32_16x16x32_bf16 v[70:73], v[178:181], v[218:221], v[70:73]
	v_mfma_f32_16x16x32_bf16 v[66:69], v[186:189], v[218:221], v[66:69]
	v_mfma_f32_16x16x32_bf16 v[118:121], v[182:185], v[198:201], v[118:121]
	v_mfma_f32_16x16x32_bf16 v[114:117], v[190:193], v[198:201], v[114:117]
	v_mfma_f32_16x16x32_bf16 v[102:105], v[182:185], v[206:209], v[102:105]
	v_mfma_f32_16x16x32_bf16 v[98:101], v[190:193], v[206:209], v[98:101]
	v_mfma_f32_16x16x32_bf16 v[86:89], v[182:185], v[214:217], v[86:89]
	v_mfma_f32_16x16x32_bf16 v[82:85], v[190:193], v[214:217], v[82:85]
	v_mfma_f32_16x16x32_bf16 v[70:73], v[182:185], v[222:225], v[70:73]
	v_mfma_f32_16x16x32_bf16 v[66:69], v[190:193], v[222:225], v[66:69]
	s_barrier
	s_mov_b32 m0, s48
	v_lshl_add_u64 v[226:227], s[16:17], 0, v[134:135]
	s_add_u32 s56, s16, 0x80000
	ds_read_b128 v[194:197], v159 offset:16384
	ds_read_b128 v[198:201], v159 offset:17408
	ds_read_b128 v[202:205], v159 offset:18432
	ds_read_b128 v[206:209], v159 offset:19456
	ds_read_b128 v[210:213], v159 offset:20480
	ds_read_b128 v[214:217], v159 offset:21504
	ds_read_b128 v[218:221], v159 offset:22528
	ds_read_b128 v[222:225], v159 offset:23552
	global_load_lds_dwordx4 v[226:227], off
	v_lshl_add_u64 v[228:229], s[16:17], 0, v[130:131]
	s_mov_b32 m0, s49
	s_addc_u32 s57, s17, 0
	global_load_lds_dwordx4 v[228:229], off
	v_lshl_add_u64 v[230:231], s[56:57], 0, v[134:135]
	s_mov_b32 m0, s50
	v_lshl_add_u64 v[232:233], s[18:19], 0, v[132:133]
	global_load_lds_dwordx4 v[230:231], off
	v_lshl_add_u64 v[230:231], s[56:57], 0, v[130:131]
	s_mov_b32 m0, s51
	s_nop 0
	global_load_lds_dwordx4 v[230:231], off
	v_lshl_add_u64 v[230:231], s[18:19], 0, v[136:137]
	s_mov_b32 m0, s36
	s_nop 0
	global_load_lds_dwordx4 v[230:231], off
	s_mov_b32 m0, s37
	s_nop 0
	global_load_lds_dwordx4 v[232:233], off
	s_waitcnt vmcnt(8)
	s_waitcnt lgkmcnt(0)
	s_barrier
	s_waitcnt lgkmcnt(0)
	v_mfma_f32_16x16x32_bf16 v[62:65], v[162:165], v[194:197], v[62:65]
	v_mfma_f32_16x16x32_bf16 v[58:61], v[170:173], v[194:197], v[58:61]
	v_mfma_f32_16x16x32_bf16 v[46:49], v[162:165], v[202:205], v[46:49]
	v_mfma_f32_16x16x32_bf16 v[42:45], v[170:173], v[202:205], v[42:45]
	v_mfma_f32_16x16x32_bf16 v[30:33], v[162:165], v[210:213], v[30:33]
	v_mfma_f32_16x16x32_bf16 v[26:29], v[170:173], v[210:213], v[26:29]
	v_mfma_f32_16x16x32_bf16 v[14:17], v[162:165], v[218:221], v[14:17]
	v_mfma_f32_16x16x32_bf16 v[10:13], v[170:173], v[218:221], v[10:13]
	v_mfma_f32_16x16x32_bf16 v[62:65], v[166:169], v[198:201], v[62:65]
	v_mfma_f32_16x16x32_bf16 v[58:61], v[174:177], v[198:201], v[58:61]
	v_mfma_f32_16x16x32_bf16 v[46:49], v[166:169], v[206:209], v[46:49]
	v_mfma_f32_16x16x32_bf16 v[42:45], v[174:177], v[206:209], v[42:45]
	v_mfma_f32_16x16x32_bf16 v[30:33], v[166:169], v[214:217], v[30:33]
	v_mfma_f32_16x16x32_bf16 v[26:29], v[174:177], v[214:217], v[26:29]
	v_mfma_f32_16x16x32_bf16 v[14:17], v[166:169], v[222:225], v[14:17]
	v_mfma_f32_16x16x32_bf16 v[10:13], v[174:177], v[222:225], v[10:13]
	v_mfma_f32_16x16x32_bf16 v[54:57], v[178:181], v[194:197], v[54:57]
	v_mfma_f32_16x16x32_bf16 v[50:53], v[186:189], v[194:197], v[50:53]
	v_mfma_f32_16x16x32_bf16 v[38:41], v[178:181], v[202:205], v[38:41]
	v_mfma_f32_16x16x32_bf16 v[34:37], v[186:189], v[202:205], v[34:37]
	v_mfma_f32_16x16x32_bf16 v[22:25], v[178:181], v[210:213], v[22:25]
	v_mfma_f32_16x16x32_bf16 v[18:21], v[186:189], v[210:213], v[18:21]
	v_mfma_f32_16x16x32_bf16 v[6:9], v[178:181], v[218:221], v[6:9]
	v_mfma_f32_16x16x32_bf16 v[2:5], v[186:189], v[218:221], v[2:5]
	v_mfma_f32_16x16x32_bf16 v[54:57], v[182:185], v[198:201], v[54:57]
	v_mfma_f32_16x16x32_bf16 v[50:53], v[190:193], v[198:201], v[50:53]
	v_mfma_f32_16x16x32_bf16 v[38:41], v[182:185], v[206:209], v[38:41]
	v_mfma_f32_16x16x32_bf16 v[34:37], v[190:193], v[206:209], v[34:37]
	v_mfma_f32_16x16x32_bf16 v[22:25], v[182:185], v[214:217], v[22:25]
	v_mfma_f32_16x16x32_bf16 v[18:21], v[190:193], v[214:217], v[18:21]
	v_mfma_f32_16x16x32_bf16 v[6:9], v[182:185], v[222:225], v[6:9]
	v_mfma_f32_16x16x32_bf16 v[2:5], v[190:193], v[222:225], v[2:5]
	s_barrier
	ds_read_b128 v[162:165], v160
	ds_read_b128 v[166:169], v160 offset:1024
	ds_read_b128 v[170:173], v160 offset:2048
	ds_read_b128 v[174:177], v160 offset:3072
	ds_read_b128 v[178:181], v161
	ds_read_b128 v[182:185], v161 offset:1024
	ds_read_b128 v[186:189], v161 offset:2048
	ds_read_b128 v[190:193], v161 offset:3072
	s_add_u32 s18, s18, 0x80000
	s_addc_u32 s19, s19, 0
	s_mov_b32 m0, s38
	v_lshl_add_u64 v[234:235], s[18:19], 0, v[136:137]
	ds_read_b128 v[194:197], v159 offset:32768
	ds_read_b128 v[198:201], v159 offset:33792
	ds_read_b128 v[202:205], v159 offset:34816
	ds_read_b128 v[206:209], v159 offset:35840
	ds_read_b128 v[210:213], v159 offset:36864
	ds_read_b128 v[214:217], v159 offset:37888
	ds_read_b128 v[218:221], v159 offset:38912
	ds_read_b128 v[222:225], v159 offset:39936
	global_load_lds_dwordx4 v[234:235], off
	v_lshl_add_u64 v[234:235], s[18:19], 0, v[132:133]
	s_mov_b32 m0, s39
	s_nop 0
	global_load_lds_dwordx4 v[234:235], off
	s_waitcnt vmcnt(8)
	s_waitcnt lgkmcnt(0)
	s_barrier
	s_waitcnt lgkmcnt(0)
	v_mfma_f32_16x16x32_bf16 v[126:129], v[162:165], v[194:197], v[126:129]
	v_mfma_f32_16x16x32_bf16 v[122:125], v[170:173], v[194:197], v[122:125]
	v_mfma_f32_16x16x32_bf16 v[110:113], v[162:165], v[202:205], v[110:113]
	v_mfma_f32_16x16x32_bf16 v[106:109], v[170:173], v[202:205], v[106:109]
	v_mfma_f32_16x16x32_bf16 v[94:97], v[162:165], v[210:213], v[94:97]
	v_mfma_f32_16x16x32_bf16 v[90:93], v[170:173], v[210:213], v[90:93]
	v_mfma_f32_16x16x32_bf16 v[78:81], v[162:165], v[218:221], v[78:81]
	v_mfma_f32_16x16x32_bf16 v[74:77], v[170:173], v[218:221], v[74:77]
	v_mfma_f32_16x16x32_bf16 v[126:129], v[166:169], v[198:201], v[126:129]
	v_mfma_f32_16x16x32_bf16 v[122:125], v[174:177], v[198:201], v[122:125]
	v_mfma_f32_16x16x32_bf16 v[110:113], v[166:169], v[206:209], v[110:113]
	v_mfma_f32_16x16x32_bf16 v[106:109], v[174:177], v[206:209], v[106:109]
	v_mfma_f32_16x16x32_bf16 v[94:97], v[166:169], v[214:217], v[94:97]
	v_mfma_f32_16x16x32_bf16 v[90:93], v[174:177], v[214:217], v[90:93]
	v_mfma_f32_16x16x32_bf16 v[78:81], v[166:169], v[222:225], v[78:81]
	v_mfma_f32_16x16x32_bf16 v[74:77], v[174:177], v[222:225], v[74:77]
	v_mfma_f32_16x16x32_bf16 v[118:121], v[178:181], v[194:197], v[118:121]
	v_mfma_f32_16x16x32_bf16 v[114:117], v[186:189], v[194:197], v[114:117]
	v_mfma_f32_16x16x32_bf16 v[102:105], v[178:181], v[202:205], v[102:105]
	v_mfma_f32_16x16x32_bf16 v[98:101], v[186:189], v[202:205], v[98:101]
	v_mfma_f32_16x16x32_bf16 v[86:89], v[178:181], v[210:213], v[86:89]
	v_mfma_f32_16x16x32_bf16 v[82:85], v[186:189], v[210:213], v[82:85]
	v_mfma_f32_16x16x32_bf16 v[70:73], v[178:181], v[218:221], v[70:73]
	v_mfma_f32_16x16x32_bf16 v[66:69], v[186:189], v[218:221], v[66:69]
	v_mfma_f32_16x16x32_bf16 v[118:121], v[182:185], v[198:201], v[118:121]
	v_mfma_f32_16x16x32_bf16 v[114:117], v[190:193], v[198:201], v[114:117]
	v_mfma_f32_16x16x32_bf16 v[102:105], v[182:185], v[206:209], v[102:105]
	v_mfma_f32_16x16x32_bf16 v[98:101], v[190:193], v[206:209], v[98:101]
	v_mfma_f32_16x16x32_bf16 v[86:89], v[182:185], v[214:217], v[86:89]
	v_mfma_f32_16x16x32_bf16 v[82:85], v[190:193], v[214:217], v[82:85]
	v_mfma_f32_16x16x32_bf16 v[70:73], v[182:185], v[222:225], v[70:73]
	v_mfma_f32_16x16x32_bf16 v[66:69], v[190:193], v[222:225], v[66:69]
	s_barrier
	s_mov_b32 m0, s52
	v_lshl_add_u64 v[226:227], v[226:227], 0, s[10:11]
	s_add_u32 s16, s16, 0x80080
	ds_read_b128 v[194:197], v159 offset:49152
	ds_read_b128 v[198:201], v159 offset:50176
	ds_read_b128 v[202:205], v159 offset:51200
	ds_read_b128 v[206:209], v159 offset:52224
	ds_read_b128 v[210:213], v159 offset:53248
	ds_read_b128 v[214:217], v159 offset:54272
	ds_read_b128 v[218:221], v159 offset:55296
	ds_read_b128 v[222:225], v159 offset:56320
	global_load_lds_dwordx4 v[226:227], off
	v_lshl_add_u64 v[226:227], v[228:229], 0, s[10:11]
	s_mov_b32 m0, s53
	s_addc_u32 s17, s17, 0
	global_load_lds_dwordx4 v[226:227], off
	v_lshl_add_u64 v[226:227], s[16:17], 0, v[134:135]
	s_mov_b32 m0, s54
	s_nop 0
	global_load_lds_dwordx4 v[226:227], off
	v_lshl_add_u64 v[226:227], s[16:17], 0, v[130:131]
	s_mov_b32 m0, s55
	s_nop 0
	global_load_lds_dwordx4 v[226:227], off
	v_lshl_add_u64 v[226:227], v[230:231], 0, s[10:11]
	s_mov_b32 m0, s41
	s_nop 0
	global_load_lds_dwordx4 v[226:227], off
	v_lshl_add_u64 v[226:227], v[232:233], 0, s[10:11]
	s_mov_b32 m0, s42
	s_nop 0
	global_load_lds_dwordx4 v[226:227], off
	s_waitcnt vmcnt(8)
	s_waitcnt lgkmcnt(0)
	s_barrier
	s_waitcnt lgkmcnt(0)
	v_mfma_f32_16x16x32_bf16 v[62:65], v[162:165], v[194:197], v[62:65]
	v_mfma_f32_16x16x32_bf16 v[58:61], v[170:173], v[194:197], v[58:61]
	v_mfma_f32_16x16x32_bf16 v[46:49], v[162:165], v[202:205], v[46:49]
	v_mfma_f32_16x16x32_bf16 v[42:45], v[170:173], v[202:205], v[42:45]
	v_mfma_f32_16x16x32_bf16 v[30:33], v[162:165], v[210:213], v[30:33]
	v_mfma_f32_16x16x32_bf16 v[26:29], v[170:173], v[210:213], v[26:29]
	v_mfma_f32_16x16x32_bf16 v[14:17], v[162:165], v[218:221], v[14:17]
	v_mfma_f32_16x16x32_bf16 v[10:13], v[170:173], v[218:221], v[10:13]
	v_mfma_f32_16x16x32_bf16 v[62:65], v[166:169], v[198:201], v[62:65]
	v_mfma_f32_16x16x32_bf16 v[58:61], v[174:177], v[198:201], v[58:61]
	v_mfma_f32_16x16x32_bf16 v[46:49], v[166:169], v[206:209], v[46:49]
	v_mfma_f32_16x16x32_bf16 v[42:45], v[174:177], v[206:209], v[42:45]
	v_mfma_f32_16x16x32_bf16 v[30:33], v[166:169], v[214:217], v[30:33]
	v_mfma_f32_16x16x32_bf16 v[26:29], v[174:177], v[214:217], v[26:29]
	v_mfma_f32_16x16x32_bf16 v[14:17], v[166:169], v[222:225], v[14:17]
	v_mfma_f32_16x16x32_bf16 v[10:13], v[174:177], v[222:225], v[10:13]
	v_mfma_f32_16x16x32_bf16 v[54:57], v[178:181], v[194:197], v[54:57]
	v_mfma_f32_16x16x32_bf16 v[50:53], v[186:189], v[194:197], v[50:53]
	v_mfma_f32_16x16x32_bf16 v[38:41], v[178:181], v[202:205], v[38:41]
	v_mfma_f32_16x16x32_bf16 v[34:37], v[186:189], v[202:205], v[34:37]
	v_mfma_f32_16x16x32_bf16 v[22:25], v[178:181], v[210:213], v[22:25]
	v_mfma_f32_16x16x32_bf16 v[18:21], v[186:189], v[210:213], v[18:21]
	v_mfma_f32_16x16x32_bf16 v[6:9], v[178:181], v[218:221], v[6:9]
	v_mfma_f32_16x16x32_bf16 v[2:5], v[186:189], v[218:221], v[2:5]
	v_mfma_f32_16x16x32_bf16 v[54:57], v[182:185], v[198:201], v[54:57]
	v_mfma_f32_16x16x32_bf16 v[50:53], v[190:193], v[198:201], v[50:53]
	v_mfma_f32_16x16x32_bf16 v[38:41], v[182:185], v[206:209], v[38:41]
	v_mfma_f32_16x16x32_bf16 v[34:37], v[190:193], v[206:209], v[34:37]
	v_mfma_f32_16x16x32_bf16 v[22:25], v[182:185], v[214:217], v[22:25]
	v_mfma_f32_16x16x32_bf16 v[18:21], v[190:193], v[214:217], v[18:21]
	v_mfma_f32_16x16x32_bf16 v[6:9], v[182:185], v[222:225], v[6:9]
	v_mfma_f32_16x16x32_bf16 v[2:5], v[190:193], v[222:225], v[2:5]
	s_barrier
	s_add_i32 s45, s45, 2
	s_add_u32 s14, s14, 0x100
	s_addc_u32 s15, s15, 0
	s_cmp_gt_u32 s45, 29
	s_cbranch_scc0 .LBB0_482
	s_lshl_b32 s4, s34, 9
	s_add_u32 s4, s6, s4
	v_mov_b32_e32 v133, 0
	v_lshl_add_u32 v130, s35, 8, v156
	s_addc_u32 s5, s7, 0
	v_lshl_or_b32 v132, s40, 6, v155
	v_mov_b32_e32 v131, v133
	v_lshl_add_u64 v[134:135], s[4:5], 0, v[132:133]
	v_mul_f32_e32 v1, 0xbfb8aa3b, v126
	v_lshlrev_b64 v[136:137], 11, v[130:131]
	v_mul_f32_e32 v131, 0xbfb8aa3b, v127
	v_mul_f32_e32 v132, 0xbfb8aa3b, v128
	v_exp_f32_e32 v1, v1
	v_exp_f32_e32 v131, v131
	v_exp_f32_e32 v132, v132
	v_mul_f32_e32 v138, 0xbfb8aa3b, v129
	v_add_f32_e32 v1, 1.0, v1
	v_add_f32_e32 v131, 1.0, v131
	v_add_f32_e32 v132, 1.0, v132
	v_rcp_f32_e32 v1, v1
	v_rcp_f32_e32 v131, v131
	v_rcp_f32_e32 v132, v132
	v_exp_f32_e32 v138, v138
	v_mul_f32_e32 v1, v126, v1
	v_mul_f32_e32 v126, v127, v131
	v_mul_f32_e32 v127, v128, v132
	v_add_f32_e32 v128, 1.0, v138
	v_mul_f32_e32 v131, 0xbfb8aa3b, v122
	v_mul_f32_e32 v132, 0xbfb8aa3b, v123
	v_rcp_f32_e32 v128, v128
	v_exp_f32_e32 v131, v131
	v_exp_f32_e32 v132, v132
	v_mul_f32_e32 v138, 0xbfb8aa3b, v125
	v_mul_f32_e32 v128, v129, v128
	v_add_f32_e32 v129, 1.0, v131
	v_add_f32_e32 v131, 1.0, v132
	v_mul_f32_e32 v132, 0xbfb8aa3b, v124
	v_exp_f32_e32 v138, v138
	v_exp_f32_e32 v132, v132
	v_rcp_f32_e32 v129, v129
	v_rcp_f32_e32 v131, v131
	v_add_f32_e32 v138, 1.0, v138
	v_add_f32_e32 v132, 1.0, v132
	v_rcp_f32_e32 v138, v138
	v_rcp_f32_e32 v132, v132
	s_mov_b64 s[4:5], 0x7ffe800
	v_lshl_add_u64 v[134:135], v[134:135], 0, s[4:5]
	v_lshl_add_u64 v[136:137], v[134:135], 0, v[136:137]
	v_mul_f32_e32 v129, v122, v129
	v_mul_f32_e32 v131, v123, v131
	v_mul_f32_e32 v125, v125, v138
	v_cvt_pk_bf16_f32 v122, v1, v126
	v_cvt_pk_bf16_f32 v123, v127, v128
	v_mul_f32_e32 v132, v124, v132
	v_mul_f32_e32 v1, 0xbfb8aa3b, v118
	v_cvt_pk_bf16_f32 v124, v129, v131
	v_cvt_pk_bf16_f32 v125, v132, v125
	global_store_dwordx4 v[136:137], v[122:125], off
	v_exp_f32_e32 v1, v1
	v_or_b32_e32 v132, 16, v130
	v_mul_f32_e32 v122, 0xbfb8aa3b, v119
	v_mul_f32_e32 v123, 0xbfb8aa3b, v120
	v_exp_f32_e32 v122, v122
	v_exp_f32_e32 v123, v123
	v_add_f32_e32 v1, 1.0, v1
	v_mul_f32_e32 v124, 0xbfb8aa3b, v121
	v_add_f32_e32 v122, 1.0, v122
	v_add_f32_e32 v123, 1.0, v123
	v_rcp_f32_e32 v1, v1
	v_rcp_f32_e32 v122, v122
	v_rcp_f32_e32 v123, v123
	v_exp_f32_e32 v124, v124
	v_mul_f32_e32 v1, v118, v1
	v_mul_f32_e32 v118, v119, v122
	v_mul_f32_e32 v119, v120, v123
	v_add_f32_e32 v120, 1.0, v124
	v_mul_f32_e32 v122, 0xbfb8aa3b, v114
	v_mul_f32_e32 v123, 0xbfb8aa3b, v115
	v_rcp_f32_e32 v120, v120
	v_exp_f32_e32 v122, v122
	v_exp_f32_e32 v123, v123
	v_mul_f32_e32 v124, 0xbfb8aa3b, v117
	v_mul_f32_e32 v120, v121, v120
	v_add_f32_e32 v121, 1.0, v122
	v_add_f32_e32 v122, 1.0, v123
	v_mul_f32_e32 v123, 0xbfb8aa3b, v116
	v_exp_f32_e32 v124, v124
	v_exp_f32_e32 v123, v123
	v_rcp_f32_e32 v121, v121
	v_rcp_f32_e32 v122, v122
	v_add_f32_e32 v124, 1.0, v124
	v_add_f32_e32 v123, 1.0, v123
	v_rcp_f32_e32 v124, v124
	v_rcp_f32_e32 v123, v123
	v_mul_f32_e32 v121, v114, v121
	v_mul_f32_e32 v122, v115, v122
	v_mul_f32_e32 v117, v117, v124
	v_mul_f32_e32 v123, v116, v123
	v_cvt_pk_bf16_f32 v114, v1, v118
	v_cvt_pk_bf16_f32 v115, v119, v120
	v_cvt_pk_bf16_f32 v116, v121, v122
	v_cvt_pk_bf16_f32 v117, v123, v117
	global_store_dwordx4 v[136:137], v[114:117], off offset:256
	v_mul_f32_e32 v1, 0xbfb8aa3b, v110
	v_exp_f32_e32 v1, v1
	v_mul_f32_e32 v116, 0xbfb8aa3b, v111
	v_mul_f32_e32 v117, 0xbfb8aa3b, v112
	v_exp_f32_e32 v116, v116
	v_exp_f32_e32 v117, v117
	v_add_f32_e32 v1, 1.0, v1
	v_mul_f32_e32 v118, 0xbfb8aa3b, v113
	v_add_f32_e32 v116, 1.0, v116
	v_add_f32_e32 v117, 1.0, v117
	v_rcp_f32_e32 v1, v1
	v_rcp_f32_e32 v116, v116
	v_rcp_f32_e32 v117, v117
	v_exp_f32_e32 v118, v118
	v_mul_f32_e32 v1, v110, v1
	v_mul_f32_e32 v110, v111, v116
	v_mul_f32_e32 v111, v112, v117
	v_add_f32_e32 v112, 1.0, v118
	v_mul_f32_e32 v116, 0xbfb8aa3b, v106
	v_mul_f32_e32 v117, 0xbfb8aa3b, v107
	v_rcp_f32_e32 v112, v112
	v_exp_f32_e32 v116, v116
	v_exp_f32_e32 v117, v117
	v_mul_f32_e32 v118, 0xbfb8aa3b, v109
	v_mul_f32_e32 v112, v113, v112
	v_add_f32_e32 v113, 1.0, v116
	v_add_f32_e32 v116, 1.0, v117
	v_mul_f32_e32 v117, 0xbfb8aa3b, v108
	v_exp_f32_e32 v118, v118
	v_exp_f32_e32 v117, v117
	v_rcp_f32_e32 v113, v113
	v_rcp_f32_e32 v116, v116
	v_add_f32_e32 v118, 1.0, v118
	v_add_f32_e32 v117, 1.0, v117
	v_rcp_f32_e32 v118, v118
	v_rcp_f32_e32 v117, v117
	v_lshlrev_b64 v[114:115], 11, v[132:133]
	v_lshl_add_u64 v[114:115], v[134:135], 0, v[114:115]
	v_mul_f32_e32 v113, v106, v113
	v_mul_f32_e32 v116, v107, v116
	v_mul_f32_e32 v109, v109, v118
	v_cvt_pk_bf16_f32 v106, v1, v110
	v_cvt_pk_bf16_f32 v107, v111, v112
	v_mul_f32_e32 v117, v108, v117
	v_mul_f32_e32 v1, 0xbfb8aa3b, v102
	v_cvt_pk_bf16_f32 v108, v113, v116
	v_cvt_pk_bf16_f32 v109, v117, v109
	global_store_dwordx4 v[114:115], v[106:109], off
	v_exp_f32_e32 v1, v1
	v_or_b32_e32 v132, 32, v130
	v_mul_f32_e32 v106, 0xbfb8aa3b, v103
	v_mul_f32_e32 v107, 0xbfb8aa3b, v104
	v_exp_f32_e32 v106, v106
	v_exp_f32_e32 v107, v107
	v_add_f32_e32 v1, 1.0, v1
	v_mul_f32_e32 v108, 0xbfb8aa3b, v105
	v_add_f32_e32 v106, 1.0, v106
	v_add_f32_e32 v107, 1.0, v107
	v_rcp_f32_e32 v1, v1
	v_rcp_f32_e32 v106, v106
	v_rcp_f32_e32 v107, v107
	v_exp_f32_e32 v108, v108
	v_mul_f32_e32 v1, v102, v1
	v_mul_f32_e32 v102, v103, v106
	v_mul_f32_e32 v103, v104, v107
	v_add_f32_e32 v104, 1.0, v108
	v_mul_f32_e32 v106, 0xbfb8aa3b, v98
	v_mul_f32_e32 v107, 0xbfb8aa3b, v99
	v_rcp_f32_e32 v104, v104
	v_exp_f32_e32 v106, v106
	v_exp_f32_e32 v107, v107
	v_mul_f32_e32 v108, 0xbfb8aa3b, v101
	v_mul_f32_e32 v104, v105, v104
	v_add_f32_e32 v105, 1.0, v106
	v_add_f32_e32 v106, 1.0, v107
	v_mul_f32_e32 v107, 0xbfb8aa3b, v100
	v_exp_f32_e32 v108, v108
	v_exp_f32_e32 v107, v107
	v_rcp_f32_e32 v105, v105
	v_rcp_f32_e32 v106, v106
	v_add_f32_e32 v108, 1.0, v108
	v_add_f32_e32 v107, 1.0, v107
	v_rcp_f32_e32 v108, v108
	v_rcp_f32_e32 v107, v107
	v_mul_f32_e32 v105, v98, v105
	v_mul_f32_e32 v106, v99, v106
	v_mul_f32_e32 v101, v101, v108
	v_mul_f32_e32 v107, v100, v107
	v_cvt_pk_bf16_f32 v98, v1, v102
	v_cvt_pk_bf16_f32 v99, v103, v104
	v_cvt_pk_bf16_f32 v100, v105, v106
	v_cvt_pk_bf16_f32 v101, v107, v101
	global_store_dwordx4 v[114:115], v[98:101], off offset:256
	v_mul_f32_e32 v1, 0xbfb8aa3b, v94
	v_exp_f32_e32 v1, v1
	v_mul_f32_e32 v100, 0xbfb8aa3b, v95
	v_mul_f32_e32 v101, 0xbfb8aa3b, v96
	v_exp_f32_e32 v100, v100
	v_exp_f32_e32 v101, v101
	v_add_f32_e32 v1, 1.0, v1
	v_mul_f32_e32 v102, 0xbfb8aa3b, v97
	v_add_f32_e32 v100, 1.0, v100
	v_add_f32_e32 v101, 1.0, v101
	v_rcp_f32_e32 v1, v1
	v_rcp_f32_e32 v100, v100
	v_rcp_f32_e32 v101, v101
	v_exp_f32_e32 v102, v102
	v_mul_f32_e32 v1, v94, v1
	v_mul_f32_e32 v94, v95, v100
	v_mul_f32_e32 v95, v96, v101
	v_add_f32_e32 v96, 1.0, v102
	v_mul_f32_e32 v100, 0xbfb8aa3b, v90
	v_mul_f32_e32 v101, 0xbfb8aa3b, v91
	v_rcp_f32_e32 v96, v96
	v_exp_f32_e32 v100, v100
	v_exp_f32_e32 v101, v101
	v_mul_f32_e32 v102, 0xbfb8aa3b, v93
	v_mul_f32_e32 v96, v97, v96
	v_add_f32_e32 v97, 1.0, v100
	v_add_f32_e32 v100, 1.0, v101
	v_mul_f32_e32 v101, 0xbfb8aa3b, v92
	v_exp_f32_e32 v102, v102
	v_exp_f32_e32 v101, v101
	v_rcp_f32_e32 v97, v97
	v_rcp_f32_e32 v100, v100
	v_add_f32_e32 v102, 1.0, v102
	v_add_f32_e32 v101, 1.0, v101
	v_rcp_f32_e32 v102, v102
	v_rcp_f32_e32 v101, v101
	v_lshlrev_b64 v[98:99], 11, v[132:133]
	v_lshl_add_u64 v[98:99], v[134:135], 0, v[98:99]
	v_mul_f32_e32 v97, v90, v97
	v_mul_f32_e32 v100, v91, v100
	v_mul_f32_e32 v93, v93, v102
	v_cvt_pk_bf16_f32 v90, v1, v94
	v_cvt_pk_bf16_f32 v91, v95, v96
	v_mul_f32_e32 v101, v92, v101
	v_mul_f32_e32 v1, 0xbfb8aa3b, v86
	v_cvt_pk_bf16_f32 v92, v97, v100
	v_cvt_pk_bf16_f32 v93, v101, v93
	global_store_dwordx4 v[98:99], v[90:93], off
	v_exp_f32_e32 v1, v1
	v_or_b32_e32 v132, 48, v130
	v_mul_f32_e32 v90, 0xbfb8aa3b, v87
	v_mul_f32_e32 v91, 0xbfb8aa3b, v88
	v_exp_f32_e32 v90, v90
	v_exp_f32_e32 v91, v91
	v_add_f32_e32 v1, 1.0, v1
	v_mul_f32_e32 v92, 0xbfb8aa3b, v89
	v_add_f32_e32 v90, 1.0, v90
	v_add_f32_e32 v91, 1.0, v91
	v_rcp_f32_e32 v1, v1
	v_rcp_f32_e32 v90, v90
	v_rcp_f32_e32 v91, v91
	v_exp_f32_e32 v92, v92
	v_mul_f32_e32 v1, v86, v1
	v_mul_f32_e32 v86, v87, v90
	v_mul_f32_e32 v87, v88, v91
	v_add_f32_e32 v88, 1.0, v92
	v_mul_f32_e32 v90, 0xbfb8aa3b, v82
	v_mul_f32_e32 v91, 0xbfb8aa3b, v83
	v_rcp_f32_e32 v88, v88
	v_exp_f32_e32 v90, v90
	v_exp_f32_e32 v91, v91
	v_mul_f32_e32 v92, 0xbfb8aa3b, v85
	v_mul_f32_e32 v88, v89, v88
	v_add_f32_e32 v89, 1.0, v90
	v_add_f32_e32 v90, 1.0, v91
	v_mul_f32_e32 v91, 0xbfb8aa3b, v84
	v_exp_f32_e32 v92, v92
	v_exp_f32_e32 v91, v91
	v_rcp_f32_e32 v89, v89
	v_rcp_f32_e32 v90, v90
	v_add_f32_e32 v92, 1.0, v92
	v_add_f32_e32 v91, 1.0, v91
	v_rcp_f32_e32 v92, v92
	v_rcp_f32_e32 v91, v91
	v_mul_f32_e32 v89, v82, v89
	v_mul_f32_e32 v90, v83, v90
	v_mul_f32_e32 v85, v85, v92
	v_mul_f32_e32 v91, v84, v91
	v_cvt_pk_bf16_f32 v82, v1, v86
	v_cvt_pk_bf16_f32 v83, v87, v88
	v_cvt_pk_bf16_f32 v84, v89, v90
	v_cvt_pk_bf16_f32 v85, v91, v85
	global_store_dwordx4 v[98:99], v[82:85], off offset:256
	v_mul_f32_e32 v1, 0xbfb8aa3b, v78
	v_exp_f32_e32 v1, v1
	v_mul_f32_e32 v84, 0xbfb8aa3b, v79
	v_mul_f32_e32 v85, 0xbfb8aa3b, v80
	v_exp_f32_e32 v84, v84
	v_exp_f32_e32 v85, v85
	v_add_f32_e32 v1, 1.0, v1
	v_mul_f32_e32 v86, 0xbfb8aa3b, v81
	v_add_f32_e32 v84, 1.0, v84
	v_add_f32_e32 v85, 1.0, v85
	v_rcp_f32_e32 v1, v1
	v_rcp_f32_e32 v84, v84
	v_rcp_f32_e32 v85, v85
	v_exp_f32_e32 v86, v86
	v_mul_f32_e32 v1, v78, v1
	v_mul_f32_e32 v78, v79, v84
	v_mul_f32_e32 v79, v80, v85
	v_add_f32_e32 v80, 1.0, v86
	v_mul_f32_e32 v84, 0xbfb8aa3b, v74
	v_mul_f32_e32 v85, 0xbfb8aa3b, v75
	v_rcp_f32_e32 v80, v80
	v_exp_f32_e32 v84, v84
	v_exp_f32_e32 v85, v85
	v_mul_f32_e32 v86, 0xbfb8aa3b, v77
	v_mul_f32_e32 v80, v81, v80
	v_add_f32_e32 v81, 1.0, v84
	v_add_f32_e32 v84, 1.0, v85
	v_mul_f32_e32 v85, 0xbfb8aa3b, v76
	v_exp_f32_e32 v86, v86
	v_exp_f32_e32 v85, v85
	v_rcp_f32_e32 v81, v81
	v_rcp_f32_e32 v84, v84
	v_add_f32_e32 v86, 1.0, v86
	v_add_f32_e32 v85, 1.0, v85
	v_rcp_f32_e32 v86, v86
	v_rcp_f32_e32 v85, v85
	v_lshlrev_b64 v[82:83], 11, v[132:133]
	v_lshl_add_u64 v[82:83], v[134:135], 0, v[82:83]
	v_mul_f32_e32 v81, v74, v81
	v_mul_f32_e32 v84, v75, v84
	v_mul_f32_e32 v77, v77, v86
	v_cvt_pk_bf16_f32 v74, v1, v78
	v_cvt_pk_bf16_f32 v75, v79, v80
	v_mul_f32_e32 v85, v76, v85
	v_mul_f32_e32 v1, 0xbfb8aa3b, v70
	v_cvt_pk_bf16_f32 v76, v81, v84
	v_cvt_pk_bf16_f32 v77, v85, v77
	global_store_dwordx4 v[82:83], v[74:77], off
	v_exp_f32_e32 v1, v1
	v_add_u32_e32 v132, 0x80, v130
	v_mul_f32_e32 v74, 0xbfb8aa3b, v71
	v_mul_f32_e32 v75, 0xbfb8aa3b, v72
	v_exp_f32_e32 v74, v74
	v_exp_f32_e32 v75, v75
	v_add_f32_e32 v1, 1.0, v1
	v_mul_f32_e32 v76, 0xbfb8aa3b, v73
	v_add_f32_e32 v74, 1.0, v74
	v_add_f32_e32 v75, 1.0, v75
	v_rcp_f32_e32 v1, v1
	v_rcp_f32_e32 v74, v74
	v_rcp_f32_e32 v75, v75
	v_exp_f32_e32 v76, v76
	v_mul_f32_e32 v1, v70, v1
	v_mul_f32_e32 v70, v71, v74
	v_mul_f32_e32 v71, v72, v75
	v_add_f32_e32 v72, 1.0, v76
	v_mul_f32_e32 v74, 0xbfb8aa3b, v66
	v_mul_f32_e32 v75, 0xbfb8aa3b, v67
	v_rcp_f32_e32 v72, v72
	v_exp_f32_e32 v74, v74
	v_exp_f32_e32 v75, v75
	v_mul_f32_e32 v76, 0xbfb8aa3b, v69
	v_mul_f32_e32 v72, v73, v72
	v_add_f32_e32 v73, 1.0, v74
	v_add_f32_e32 v74, 1.0, v75
	v_mul_f32_e32 v75, 0xbfb8aa3b, v68
	v_exp_f32_e32 v76, v76
	v_exp_f32_e32 v75, v75
	v_rcp_f32_e32 v73, v73
	v_rcp_f32_e32 v74, v74
	v_add_f32_e32 v76, 1.0, v76
	v_add_f32_e32 v75, 1.0, v75
	v_rcp_f32_e32 v76, v76
	v_rcp_f32_e32 v75, v75
	v_mul_f32_e32 v73, v66, v73
	v_mul_f32_e32 v74, v67, v74
	v_mul_f32_e32 v69, v69, v76
	v_mul_f32_e32 v75, v68, v75
	v_cvt_pk_bf16_f32 v66, v1, v70
	v_cvt_pk_bf16_f32 v67, v71, v72
	v_cvt_pk_bf16_f32 v68, v73, v74
	v_cvt_pk_bf16_f32 v69, v75, v69
	global_store_dwordx4 v[82:83], v[66:69], off offset:256
	v_mul_f32_e32 v1, 0xbfb8aa3b, v62
	v_exp_f32_e32 v1, v1
	v_mul_f32_e32 v68, 0xbfb8aa3b, v63
	v_mul_f32_e32 v69, 0xbfb8aa3b, v64
	v_exp_f32_e32 v68, v68
	v_exp_f32_e32 v69, v69
	v_add_f32_e32 v1, 1.0, v1
	v_mul_f32_e32 v70, 0xbfb8aa3b, v65
	v_add_f32_e32 v68, 1.0, v68
	v_add_f32_e32 v69, 1.0, v69
	v_rcp_f32_e32 v1, v1
	v_rcp_f32_e32 v68, v68
	v_rcp_f32_e32 v69, v69
	v_exp_f32_e32 v70, v70
	v_mul_f32_e32 v1, v62, v1
	v_mul_f32_e32 v62, v63, v68
	v_mul_f32_e32 v63, v64, v69
	v_add_f32_e32 v64, 1.0, v70
	v_mul_f32_e32 v68, 0xbfb8aa3b, v58
	v_mul_f32_e32 v69, 0xbfb8aa3b, v59
	v_rcp_f32_e32 v64, v64
	v_exp_f32_e32 v68, v68
	v_exp_f32_e32 v69, v69
	v_mul_f32_e32 v70, 0xbfb8aa3b, v61
	v_mul_f32_e32 v64, v65, v64
	v_add_f32_e32 v65, 1.0, v68
	v_add_f32_e32 v68, 1.0, v69
	v_mul_f32_e32 v69, 0xbfb8aa3b, v60
	v_exp_f32_e32 v70, v70
	v_exp_f32_e32 v69, v69
	v_rcp_f32_e32 v65, v65
	v_rcp_f32_e32 v68, v68
	v_add_f32_e32 v70, 1.0, v70
	v_add_f32_e32 v69, 1.0, v69
	v_rcp_f32_e32 v70, v70
	v_rcp_f32_e32 v69, v69
	v_lshlrev_b64 v[66:67], 11, v[132:133]
	v_lshl_add_u64 v[66:67], v[134:135], 0, v[66:67]
	v_mul_f32_e32 v65, v58, v65
	v_mul_f32_e32 v68, v59, v68
	v_mul_f32_e32 v61, v61, v70
	v_cvt_pk_bf16_f32 v58, v1, v62
	v_cvt_pk_bf16_f32 v59, v63, v64
	v_mul_f32_e32 v69, v60, v69
	v_mul_f32_e32 v1, 0xbfb8aa3b, v54
	v_cvt_pk_bf16_f32 v60, v65, v68
	v_cvt_pk_bf16_f32 v61, v69, v61
	global_store_dwordx4 v[66:67], v[58:61], off
	v_exp_f32_e32 v1, v1
	v_add_u32_e32 v132, 0x90, v130
	v_mul_f32_e32 v58, 0xbfb8aa3b, v55
	v_mul_f32_e32 v59, 0xbfb8aa3b, v56
	v_exp_f32_e32 v58, v58
	v_exp_f32_e32 v59, v59
	v_add_f32_e32 v1, 1.0, v1
	v_mul_f32_e32 v60, 0xbfb8aa3b, v57
	v_add_f32_e32 v58, 1.0, v58
	v_add_f32_e32 v59, 1.0, v59
	v_rcp_f32_e32 v1, v1
	v_rcp_f32_e32 v58, v58
	v_rcp_f32_e32 v59, v59
	v_exp_f32_e32 v60, v60
	v_mul_f32_e32 v1, v54, v1
	v_mul_f32_e32 v54, v55, v58
	v_mul_f32_e32 v55, v56, v59
	v_add_f32_e32 v56, 1.0, v60
	v_mul_f32_e32 v58, 0xbfb8aa3b, v50
	v_mul_f32_e32 v59, 0xbfb8aa3b, v51
	v_rcp_f32_e32 v56, v56
	v_exp_f32_e32 v58, v58
	v_exp_f32_e32 v59, v59
	v_mul_f32_e32 v60, 0xbfb8aa3b, v53
	v_mul_f32_e32 v56, v57, v56
	v_add_f32_e32 v57, 1.0, v58
	v_add_f32_e32 v58, 1.0, v59
	v_mul_f32_e32 v59, 0xbfb8aa3b, v52
	v_exp_f32_e32 v60, v60
	v_exp_f32_e32 v59, v59
	v_rcp_f32_e32 v57, v57
	v_rcp_f32_e32 v58, v58
	v_add_f32_e32 v60, 1.0, v60
	v_add_f32_e32 v59, 1.0, v59
	v_rcp_f32_e32 v60, v60
	v_rcp_f32_e32 v59, v59
	v_mul_f32_e32 v57, v50, v57
	v_mul_f32_e32 v58, v51, v58
	v_mul_f32_e32 v53, v53, v60
	v_mul_f32_e32 v59, v52, v59
	v_cvt_pk_bf16_f32 v50, v1, v54
	v_cvt_pk_bf16_f32 v51, v55, v56
	v_cvt_pk_bf16_f32 v52, v57, v58
	v_cvt_pk_bf16_f32 v53, v59, v53
	global_store_dwordx4 v[66:67], v[50:53], off offset:256
	v_mul_f32_e32 v1, 0xbfb8aa3b, v46
	v_exp_f32_e32 v1, v1
	v_mul_f32_e32 v52, 0xbfb8aa3b, v47
	v_mul_f32_e32 v53, 0xbfb8aa3b, v48
	v_exp_f32_e32 v52, v52
	v_exp_f32_e32 v53, v53
	v_add_f32_e32 v1, 1.0, v1
	v_mul_f32_e32 v54, 0xbfb8aa3b, v49
	v_add_f32_e32 v52, 1.0, v52
	v_add_f32_e32 v53, 1.0, v53
	v_rcp_f32_e32 v1, v1
	v_rcp_f32_e32 v52, v52
	v_rcp_f32_e32 v53, v53
	v_exp_f32_e32 v54, v54
	v_mul_f32_e32 v1, v46, v1
	v_mul_f32_e32 v46, v47, v52
	v_mul_f32_e32 v47, v48, v53
	v_add_f32_e32 v48, 1.0, v54
	v_mul_f32_e32 v52, 0xbfb8aa3b, v42
	v_mul_f32_e32 v53, 0xbfb8aa3b, v43
	v_rcp_f32_e32 v48, v48
	v_exp_f32_e32 v52, v52
	v_exp_f32_e32 v53, v53
	v_mul_f32_e32 v54, 0xbfb8aa3b, v45
	v_mul_f32_e32 v48, v49, v48
	v_add_f32_e32 v49, 1.0, v52
	v_add_f32_e32 v52, 1.0, v53
	v_mul_f32_e32 v53, 0xbfb8aa3b, v44
	v_exp_f32_e32 v54, v54
	v_exp_f32_e32 v53, v53
	v_rcp_f32_e32 v49, v49
	v_rcp_f32_e32 v52, v52
	v_add_f32_e32 v54, 1.0, v54
	v_add_f32_e32 v53, 1.0, v53
	v_rcp_f32_e32 v54, v54
	v_rcp_f32_e32 v53, v53
	v_lshlrev_b64 v[50:51], 11, v[132:133]
	v_lshl_add_u64 v[50:51], v[134:135], 0, v[50:51]
	v_mul_f32_e32 v49, v42, v49
	v_mul_f32_e32 v52, v43, v52
	v_mul_f32_e32 v45, v45, v54
	v_cvt_pk_bf16_f32 v42, v1, v46
	v_cvt_pk_bf16_f32 v43, v47, v48
	v_mul_f32_e32 v53, v44, v53
	v_mul_f32_e32 v1, 0xbfb8aa3b, v38
	v_cvt_pk_bf16_f32 v44, v49, v52
	v_cvt_pk_bf16_f32 v45, v53, v45
	global_store_dwordx4 v[50:51], v[42:45], off
	v_exp_f32_e32 v1, v1
	v_add_u32_e32 v132, 0xa0, v130
	v_mul_f32_e32 v42, 0xbfb8aa3b, v39
	v_mul_f32_e32 v43, 0xbfb8aa3b, v40
	v_exp_f32_e32 v42, v42
	v_exp_f32_e32 v43, v43
	v_add_f32_e32 v1, 1.0, v1
	v_mul_f32_e32 v44, 0xbfb8aa3b, v41
	v_add_f32_e32 v42, 1.0, v42
	v_add_f32_e32 v43, 1.0, v43
	v_rcp_f32_e32 v1, v1
	v_rcp_f32_e32 v42, v42
	v_rcp_f32_e32 v43, v43
	v_exp_f32_e32 v44, v44
	v_mul_f32_e32 v1, v38, v1
	v_mul_f32_e32 v38, v39, v42
	v_mul_f32_e32 v39, v40, v43
	v_add_f32_e32 v40, 1.0, v44
	v_mul_f32_e32 v42, 0xbfb8aa3b, v34
	v_mul_f32_e32 v43, 0xbfb8aa3b, v35
	v_rcp_f32_e32 v40, v40
	v_exp_f32_e32 v42, v42
	v_exp_f32_e32 v43, v43
	v_mul_f32_e32 v44, 0xbfb8aa3b, v37
	v_mul_f32_e32 v40, v41, v40
	v_add_f32_e32 v41, 1.0, v42
	v_add_f32_e32 v42, 1.0, v43
	v_mul_f32_e32 v43, 0xbfb8aa3b, v36
	v_exp_f32_e32 v44, v44
	v_exp_f32_e32 v43, v43
	v_rcp_f32_e32 v41, v41
	v_rcp_f32_e32 v42, v42
	v_add_f32_e32 v44, 1.0, v44
	v_add_f32_e32 v43, 1.0, v43
	v_rcp_f32_e32 v44, v44
	v_rcp_f32_e32 v43, v43
	v_mul_f32_e32 v41, v34, v41
	v_mul_f32_e32 v42, v35, v42
	v_mul_f32_e32 v37, v37, v44
	v_mul_f32_e32 v43, v36, v43
	v_cvt_pk_bf16_f32 v34, v1, v38
	v_cvt_pk_bf16_f32 v35, v39, v40
	v_cvt_pk_bf16_f32 v36, v41, v42
	v_cvt_pk_bf16_f32 v37, v43, v37
	global_store_dwordx4 v[50:51], v[34:37], off offset:256
	v_mul_f32_e32 v1, 0xbfb8aa3b, v30
	v_exp_f32_e32 v1, v1
	v_mul_f32_e32 v36, 0xbfb8aa3b, v31
	v_mul_f32_e32 v37, 0xbfb8aa3b, v32
	v_exp_f32_e32 v36, v36
	v_exp_f32_e32 v37, v37
	v_add_f32_e32 v1, 1.0, v1
	v_mul_f32_e32 v38, 0xbfb8aa3b, v33
	v_add_f32_e32 v36, 1.0, v36
	v_add_f32_e32 v37, 1.0, v37
	v_rcp_f32_e32 v1, v1
	v_rcp_f32_e32 v36, v36
	v_rcp_f32_e32 v37, v37
	v_exp_f32_e32 v38, v38
	v_mul_f32_e32 v1, v30, v1
	v_mul_f32_e32 v30, v31, v36
	v_mul_f32_e32 v31, v32, v37
	v_add_f32_e32 v32, 1.0, v38
	v_mul_f32_e32 v36, 0xbfb8aa3b, v26
	v_mul_f32_e32 v37, 0xbfb8aa3b, v27
	v_rcp_f32_e32 v32, v32
	v_exp_f32_e32 v36, v36
	v_exp_f32_e32 v37, v37
	v_mul_f32_e32 v38, 0xbfb8aa3b, v29
	v_mul_f32_e32 v32, v33, v32
	v_add_f32_e32 v33, 1.0, v36
	v_add_f32_e32 v36, 1.0, v37
	v_mul_f32_e32 v37, 0xbfb8aa3b, v28
	v_exp_f32_e32 v38, v38
	v_exp_f32_e32 v37, v37
	v_rcp_f32_e32 v33, v33
	v_rcp_f32_e32 v36, v36
	v_add_f32_e32 v38, 1.0, v38
	v_add_f32_e32 v37, 1.0, v37
	v_rcp_f32_e32 v38, v38
	v_rcp_f32_e32 v37, v37
	v_lshlrev_b64 v[34:35], 11, v[132:133]
	v_lshl_add_u64 v[34:35], v[134:135], 0, v[34:35]
	v_mul_f32_e32 v33, v26, v33
	v_mul_f32_e32 v36, v27, v36
	v_mul_f32_e32 v29, v29, v38
	v_cvt_pk_bf16_f32 v26, v1, v30
	v_cvt_pk_bf16_f32 v27, v31, v32
	v_mul_f32_e32 v37, v28, v37
	v_mul_f32_e32 v1, 0xbfb8aa3b, v22
	v_cvt_pk_bf16_f32 v28, v33, v36
	v_cvt_pk_bf16_f32 v29, v37, v29
	global_store_dwordx4 v[34:35], v[26:29], off
	v_exp_f32_e32 v1, v1
	v_add_u32_e32 v132, 0xb0, v130
	v_mul_f32_e32 v26, 0xbfb8aa3b, v23
	v_mul_f32_e32 v27, 0xbfb8aa3b, v24
	v_exp_f32_e32 v26, v26
	v_exp_f32_e32 v27, v27
	v_add_f32_e32 v1, 1.0, v1
	v_mul_f32_e32 v28, 0xbfb8aa3b, v25
	v_add_f32_e32 v26, 1.0, v26
	v_add_f32_e32 v27, 1.0, v27
	v_rcp_f32_e32 v1, v1
	v_rcp_f32_e32 v26, v26
	v_rcp_f32_e32 v27, v27
	v_exp_f32_e32 v28, v28
	v_mul_f32_e32 v1, v22, v1
	v_mul_f32_e32 v22, v23, v26
	v_mul_f32_e32 v23, v24, v27
	v_add_f32_e32 v24, 1.0, v28
	v_mul_f32_e32 v26, 0xbfb8aa3b, v18
	v_mul_f32_e32 v27, 0xbfb8aa3b, v19
	v_rcp_f32_e32 v24, v24
	v_exp_f32_e32 v26, v26
	v_exp_f32_e32 v27, v27
	v_mul_f32_e32 v28, 0xbfb8aa3b, v21
	v_mul_f32_e32 v24, v25, v24
	v_add_f32_e32 v25, 1.0, v26
	v_add_f32_e32 v26, 1.0, v27
	v_mul_f32_e32 v27, 0xbfb8aa3b, v20
	v_exp_f32_e32 v28, v28
	v_exp_f32_e32 v27, v27
	v_rcp_f32_e32 v25, v25
	v_rcp_f32_e32 v26, v26
	v_add_f32_e32 v28, 1.0, v28
	v_add_f32_e32 v27, 1.0, v27
	v_rcp_f32_e32 v28, v28
	v_rcp_f32_e32 v27, v27
	v_mul_f32_e32 v25, v18, v25
	v_mul_f32_e32 v26, v19, v26
	v_mul_f32_e32 v21, v21, v28
	v_mul_f32_e32 v27, v20, v27
	v_cvt_pk_bf16_f32 v18, v1, v22
	v_cvt_pk_bf16_f32 v19, v23, v24
	v_cvt_pk_bf16_f32 v20, v25, v26
	v_cvt_pk_bf16_f32 v21, v27, v21
	global_store_dwordx4 v[34:35], v[18:21], off offset:256
	v_mul_f32_e32 v1, 0xbfb8aa3b, v14
	v_exp_f32_e32 v1, v1
	v_mul_f32_e32 v20, 0xbfb8aa3b, v15
	v_mul_f32_e32 v21, 0xbfb8aa3b, v16
	v_exp_f32_e32 v20, v20
	v_exp_f32_e32 v21, v21
	v_add_f32_e32 v1, 1.0, v1
	v_mul_f32_e32 v22, 0xbfb8aa3b, v17
	v_add_f32_e32 v20, 1.0, v20
	v_add_f32_e32 v21, 1.0, v21
	v_rcp_f32_e32 v1, v1
	v_rcp_f32_e32 v20, v20
	v_rcp_f32_e32 v21, v21
	v_exp_f32_e32 v22, v22
	v_mul_f32_e32 v1, v14, v1
	v_mul_f32_e32 v14, v15, v20
	v_mul_f32_e32 v15, v16, v21
	v_add_f32_e32 v16, 1.0, v22
	v_mul_f32_e32 v20, 0xbfb8aa3b, v10
	v_mul_f32_e32 v21, 0xbfb8aa3b, v11
	v_rcp_f32_e32 v16, v16
	v_exp_f32_e32 v20, v20
	v_exp_f32_e32 v21, v21
	v_mul_f32_e32 v22, 0xbfb8aa3b, v13
	v_mul_f32_e32 v16, v17, v16
	v_add_f32_e32 v17, 1.0, v20
	v_add_f32_e32 v20, 1.0, v21
	v_mul_f32_e32 v21, 0xbfb8aa3b, v12
	v_exp_f32_e32 v22, v22
	v_exp_f32_e32 v21, v21
	v_rcp_f32_e32 v17, v17
	v_rcp_f32_e32 v20, v20
	v_add_f32_e32 v22, 1.0, v22
	v_add_f32_e32 v21, 1.0, v21
	v_rcp_f32_e32 v22, v22
	v_rcp_f32_e32 v21, v21
	v_lshlrev_b64 v[18:19], 11, v[132:133]
	v_lshl_add_u64 v[18:19], v[134:135], 0, v[18:19]
	v_mul_f32_e32 v17, v10, v17
	v_mul_f32_e32 v20, v11, v20
	v_mul_f32_e32 v13, v13, v22
	v_cvt_pk_bf16_f32 v10, v1, v14
	v_cvt_pk_bf16_f32 v11, v15, v16
	v_mul_f32_e32 v21, v12, v21
	v_mul_f32_e32 v1, 0xbfb8aa3b, v6
	v_cvt_pk_bf16_f32 v12, v17, v20
	v_cvt_pk_bf16_f32 v13, v21, v13
	global_store_dwordx4 v[18:19], v[10:13], off
	v_exp_f32_e32 v1, v1
	s_cmpk_lt_u32 s23, 0x100
	v_mul_f32_e32 v10, 0xbfb8aa3b, v7
	v_mul_f32_e32 v11, 0xbfb8aa3b, v8
	v_exp_f32_e32 v10, v10
	v_exp_f32_e32 v11, v11
	v_add_f32_e32 v1, 1.0, v1
	v_mul_f32_e32 v12, 0xbfb8aa3b, v9
	v_add_f32_e32 v10, 1.0, v10
	v_add_f32_e32 v11, 1.0, v11
	v_rcp_f32_e32 v1, v1
	v_rcp_f32_e32 v10, v10
	v_rcp_f32_e32 v11, v11
	v_exp_f32_e32 v12, v12
	v_mul_f32_e32 v1, v6, v1
	v_mul_f32_e32 v6, v7, v10
	v_mul_f32_e32 v7, v8, v11
	v_add_f32_e32 v8, 1.0, v12
	v_mul_f32_e32 v10, 0xbfb8aa3b, v2
	v_mul_f32_e32 v11, 0xbfb8aa3b, v3
	v_rcp_f32_e32 v8, v8
	v_exp_f32_e32 v10, v10
	v_exp_f32_e32 v11, v11
	v_mul_f32_e32 v12, 0xbfb8aa3b, v5
	v_mul_f32_e32 v8, v9, v8
	v_add_f32_e32 v9, 1.0, v10
	v_add_f32_e32 v10, 1.0, v11
	v_mul_f32_e32 v11, 0xbfb8aa3b, v4
	v_exp_f32_e32 v12, v12
	v_exp_f32_e32 v11, v11
	v_rcp_f32_e32 v9, v9
	v_rcp_f32_e32 v10, v10
	v_add_f32_e32 v12, 1.0, v12
	v_add_f32_e32 v11, 1.0, v11
	v_rcp_f32_e32 v12, v12
	v_rcp_f32_e32 v11, v11
	v_mul_f32_e32 v9, v2, v9
	v_mul_f32_e32 v10, v3, v10
	v_mul_f32_e32 v5, v5, v12
	v_mul_f32_e32 v11, v4, v11
	v_cvt_pk_bf16_f32 v2, v1, v6
	v_cvt_pk_bf16_f32 v3, v7, v8
	v_cvt_pk_bf16_f32 v4, v9, v10
	v_cvt_pk_bf16_f32 v5, v11, v5
	global_store_dwordx4 v[18:19], v[2:5], off offset:256
	s_waitcnt vmcnt(0)
	s_cbranch_scc0 .LBB0_485
	s_barrier

.LBB0_505:
	ds_read_b128 v[148:151], v143
	ds_read_b128 v[152:155], v143 offset:1024
	ds_read_b128 v[156:159], v143 offset:2048
	ds_read_b128 v[160:163], v143 offset:3072
	ds_read_b128 v[164:167], v144
	ds_read_b128 v[168:171], v144 offset:1024
	ds_read_b128 v[172:175], v144 offset:2048
	ds_read_b128 v[176:179], v144 offset:3072
	s_add_u32 s18, s14, s16
	s_addc_u32 s19, s15, s17
	s_add_u32 s18, s18, 0xd000100
	s_addc_u32 s19, s19, 0
	s_add_u32 s53, s40, s16
	s_addc_u32 s54, s41, s17
	s_cmpk_eq_i32 s16, 0x700
	s_cselect_b32 s21, s11, s19
	s_cselect_b32 s20, s10, s18
	s_cselect_b32 s19, s9, s54
	s_cselect_b32 s18, s8, s53
	s_mov_b32 m0, s43
	v_lshl_add_u64 v[212:213], v[140:141], 0, s[16:17]
	ds_read_b128 v[180:183], v145
	ds_read_b128 v[184:187], v145 offset:1024
	ds_read_b128 v[188:191], v145 offset:2048
	ds_read_b128 v[192:195], v145 offset:3072
	ds_read_b128 v[196:199], v145 offset:4096
	ds_read_b128 v[200:203], v145 offset:5120
	ds_read_b128 v[204:207], v145 offset:6144
	ds_read_b128 v[208:211], v145 offset:7168
	global_load_lds_dwordx4 v[212:213], off
	v_lshl_add_u64 v[212:213], v[138:139], 0, s[16:17]
	s_mov_b32 m0, s44
	s_nop 0
	global_load_lds_dwordx4 v[212:213], off
	s_waitcnt vmcnt(8)
	s_waitcnt lgkmcnt(0)
	s_barrier
	s_waitcnt lgkmcnt(0)
	v_mfma_f32_16x16x32_bf16 v[130:133], v[148:151], v[180:183], v[130:133]
	v_mfma_f32_16x16x32_bf16 v[134:137], v[156:159], v[180:183], v[134:137]
	v_mfma_f32_16x16x32_bf16 v[110:113], v[148:151], v[188:191], v[110:113]
	v_mfma_f32_16x16x32_bf16 v[106:109], v[156:159], v[188:191], v[106:109]
	v_mfma_f32_16x16x32_bf16 v[94:97], v[148:151], v[196:199], v[94:97]
	v_mfma_f32_16x16x32_bf16 v[90:93], v[156:159], v[196:199], v[90:93]
	v_mfma_f32_16x16x32_bf16 v[78:81], v[148:151], v[204:207], v[78:81]
	v_mfma_f32_16x16x32_bf16 v[74:77], v[156:159], v[204:207], v[74:77]
	v_mfma_f32_16x16x32_bf16 v[130:133], v[152:155], v[184:187], v[130:133]
	v_mfma_f32_16x16x32_bf16 v[134:137], v[160:163], v[184:187], v[134:137]
	v_mfma_f32_16x16x32_bf16 v[110:113], v[152:155], v[192:195], v[110:113]
	v_mfma_f32_16x16x32_bf16 v[106:109], v[160:163], v[192:195], v[106:109]
	v_mfma_f32_16x16x32_bf16 v[94:97], v[152:155], v[200:203], v[94:97]
	v_mfma_f32_16x16x32_bf16 v[90:93], v[160:163], v[200:203], v[90:93]
	v_mfma_f32_16x16x32_bf16 v[78:81], v[152:155], v[208:211], v[78:81]
	v_mfma_f32_16x16x32_bf16 v[74:77], v[160:163], v[208:211], v[74:77]
	v_mfma_f32_16x16x32_bf16 v[118:121], v[164:167], v[180:183], v[118:121]
	v_mfma_f32_16x16x32_bf16 v[114:117], v[172:175], v[180:183], v[114:117]
	v_mfma_f32_16x16x32_bf16 v[102:105], v[164:167], v[188:191], v[102:105]
	v_mfma_f32_16x16x32_bf16 v[98:101], v[172:175], v[188:191], v[98:101]
	v_mfma_f32_16x16x32_bf16 v[86:89], v[164:167], v[196:199], v[86:89]
	v_mfma_f32_16x16x32_bf16 v[82:85], v[172:175], v[196:199], v[82:85]
	v_mfma_f32_16x16x32_bf16 v[70:73], v[164:167], v[204:207], v[70:73]
	v_mfma_f32_16x16x32_bf16 v[66:69], v[172:175], v[204:207], v[66:69]
	v_mfma_f32_16x16x32_bf16 v[118:121], v[168:171], v[184:187], v[118:121]
	v_mfma_f32_16x16x32_bf16 v[114:117], v[176:179], v[184:187], v[114:117]
	v_mfma_f32_16x16x32_bf16 v[102:105], v[168:171], v[192:195], v[102:105]
	v_mfma_f32_16x16x32_bf16 v[98:101], v[176:179], v[192:195], v[98:101]
	v_mfma_f32_16x16x32_bf16 v[86:89], v[168:171], v[200:203], v[86:89]
	v_mfma_f32_16x16x32_bf16 v[82:85], v[176:179], v[200:203], v[82:85]
	v_mfma_f32_16x16x32_bf16 v[70:73], v[168:171], v[208:211], v[70:73]
	v_mfma_f32_16x16x32_bf16 v[66:69], v[176:179], v[208:211], v[66:69]
	s_barrier
	s_mov_b32 m0, s45
	v_lshl_add_u64 v[212:213], s[18:19], 0, v[126:127]
	s_add_u32 s54, s18, 0x40000
	ds_read_b128 v[180:183], v145 offset:16384
	ds_read_b128 v[184:187], v145 offset:17408
	ds_read_b128 v[188:191], v145 offset:18432
	ds_read_b128 v[192:195], v145 offset:19456
	ds_read_b128 v[196:199], v145 offset:20480
	ds_read_b128 v[200:203], v145 offset:21504
	ds_read_b128 v[204:207], v145 offset:22528
	ds_read_b128 v[208:211], v145 offset:23552
	global_load_lds_dwordx4 v[212:213], off
	v_lshl_add_u64 v[214:215], s[18:19], 0, v[122:123]
	s_mov_b32 m0, s46
	s_addc_u32 s55, s19, 0
	global_load_lds_dwordx4 v[214:215], off
	v_lshl_add_u64 v[216:217], s[54:55], 0, v[126:127]
	s_mov_b32 m0, s47
	v_lshl_add_u64 v[218:219], s[20:21], 0, v[124:125]
	global_load_lds_dwordx4 v[216:217], off
	v_lshl_add_u64 v[216:217], s[54:55], 0, v[122:123]
	s_mov_b32 m0, s48
	s_nop 0
	global_load_lds_dwordx4 v[216:217], off
	v_lshl_add_u64 v[216:217], s[20:21], 0, v[128:129]
	s_mov_b32 m0, s5
	s_nop 0
	global_load_lds_dwordx4 v[216:217], off
	s_mov_b32 m0, s34
	s_nop 0
	global_load_lds_dwordx4 v[218:219], off
	s_waitcnt vmcnt(8)
	s_waitcnt lgkmcnt(0)
	s_barrier
	s_waitcnt lgkmcnt(0)
	v_mfma_f32_16x16x32_bf16 v[62:65], v[148:151], v[180:183], v[62:65]
	v_mfma_f32_16x16x32_bf16 v[58:61], v[156:159], v[180:183], v[58:61]
	v_mfma_f32_16x16x32_bf16 v[46:49], v[148:151], v[188:191], v[46:49]
	v_mfma_f32_16x16x32_bf16 v[42:45], v[156:159], v[188:191], v[42:45]
	v_mfma_f32_16x16x32_bf16 v[30:33], v[148:151], v[196:199], v[30:33]
	v_mfma_f32_16x16x32_bf16 v[26:29], v[156:159], v[196:199], v[26:29]
	v_mfma_f32_16x16x32_bf16 v[14:17], v[148:151], v[204:207], v[14:17]
	v_mfma_f32_16x16x32_bf16 v[10:13], v[156:159], v[204:207], v[10:13]
	v_mfma_f32_16x16x32_bf16 v[62:65], v[152:155], v[184:187], v[62:65]
	v_mfma_f32_16x16x32_bf16 v[58:61], v[160:163], v[184:187], v[58:61]
	v_mfma_f32_16x16x32_bf16 v[46:49], v[152:155], v[192:195], v[46:49]
	v_mfma_f32_16x16x32_bf16 v[42:45], v[160:163], v[192:195], v[42:45]
	v_mfma_f32_16x16x32_bf16 v[30:33], v[152:155], v[200:203], v[30:33]
	v_mfma_f32_16x16x32_bf16 v[26:29], v[160:163], v[200:203], v[26:29]
	v_mfma_f32_16x16x32_bf16 v[14:17], v[152:155], v[208:211], v[14:17]
	v_mfma_f32_16x16x32_bf16 v[10:13], v[160:163], v[208:211], v[10:13]
	v_mfma_f32_16x16x32_bf16 v[54:57], v[164:167], v[180:183], v[54:57]
	v_mfma_f32_16x16x32_bf16 v[50:53], v[172:175], v[180:183], v[50:53]
	v_mfma_f32_16x16x32_bf16 v[38:41], v[164:167], v[188:191], v[38:41]
	v_mfma_f32_16x16x32_bf16 v[34:37], v[172:175], v[188:191], v[34:37]
	v_mfma_f32_16x16x32_bf16 v[22:25], v[164:167], v[196:199], v[22:25]
	v_mfma_f32_16x16x32_bf16 v[18:21], v[172:175], v[196:199], v[18:21]
	v_mfma_f32_16x16x32_bf16 v[6:9], v[164:167], v[204:207], v[6:9]
	v_mfma_f32_16x16x32_bf16 v[2:5], v[172:175], v[204:207], v[2:5]
	v_mfma_f32_16x16x32_bf16 v[54:57], v[168:171], v[184:187], v[54:57]
	v_mfma_f32_16x16x32_bf16 v[50:53], v[176:179], v[184:187], v[50:53]
	v_mfma_f32_16x16x32_bf16 v[38:41], v[168:171], v[192:195], v[38:41]
	v_mfma_f32_16x16x32_bf16 v[34:37], v[176:179], v[192:195], v[34:37]
	v_mfma_f32_16x16x32_bf16 v[22:25], v[168:171], v[200:203], v[22:25]
	v_mfma_f32_16x16x32_bf16 v[18:21], v[176:179], v[200:203], v[18:21]
	v_mfma_f32_16x16x32_bf16 v[6:9], v[168:171], v[208:211], v[6:9]
	v_mfma_f32_16x16x32_bf16 v[2:5], v[176:179], v[208:211], v[2:5]
	s_barrier
	ds_read_b128 v[148:151], v146
	ds_read_b128 v[152:155], v146 offset:1024
	ds_read_b128 v[156:159], v146 offset:2048
	ds_read_b128 v[160:163], v146 offset:3072
	ds_read_b128 v[164:167], v147
	ds_read_b128 v[168:171], v147 offset:1024
	ds_read_b128 v[172:175], v147 offset:2048
	ds_read_b128 v[176:179], v147 offset:3072
	s_add_u32 s20, s20, 0x40000
	s_addc_u32 s21, s21, 0
	s_mov_b32 m0, s35
	v_lshl_add_u64 v[220:221], s[20:21], 0, v[128:129]
	ds_read_b128 v[180:183], v145 offset:32768
	ds_read_b128 v[184:187], v145 offset:33792
	ds_read_b128 v[188:191], v145 offset:34816
	ds_read_b128 v[192:195], v145 offset:35840
	ds_read_b128 v[196:199], v145 offset:36864
	ds_read_b128 v[200:203], v145 offset:37888
	ds_read_b128 v[204:207], v145 offset:38912
	ds_read_b128 v[208:211], v145 offset:39936
	global_load_lds_dwordx4 v[220:221], off
	v_lshl_add_u64 v[220:221], s[20:21], 0, v[124:125]
	s_mov_b32 m0, s36
	s_nop 0
	global_load_lds_dwordx4 v[220:221], off
	s_waitcnt vmcnt(8)
	s_waitcnt lgkmcnt(0)
	s_barrier
	s_waitcnt lgkmcnt(0)
	v_mfma_f32_16x16x32_bf16 v[130:133], v[148:151], v[180:183], v[130:133]
	v_mfma_f32_16x16x32_bf16 v[134:137], v[156:159], v[180:183], v[134:137]
	v_mfma_f32_16x16x32_bf16 v[110:113], v[148:151], v[188:191], v[110:113]
	v_mfma_f32_16x16x32_bf16 v[106:109], v[156:159], v[188:191], v[106:109]
	v_mfma_f32_16x16x32_bf16 v[94:97], v[148:151], v[196:199], v[94:97]
	v_mfma_f32_16x16x32_bf16 v[90:93], v[156:159], v[196:199], v[90:93]
	v_mfma_f32_16x16x32_bf16 v[78:81], v[148:151], v[204:207], v[78:81]
	v_mfma_f32_16x16x32_bf16 v[74:77], v[156:159], v[204:207], v[74:77]
	v_mfma_f32_16x16x32_bf16 v[130:133], v[152:155], v[184:187], v[130:133]
	v_mfma_f32_16x16x32_bf16 v[134:137], v[160:163], v[184:187], v[134:137]
	v_mfma_f32_16x16x32_bf16 v[110:113], v[152:155], v[192:195], v[110:113]
	v_mfma_f32_16x16x32_bf16 v[106:109], v[160:163], v[192:195], v[106:109]
	v_mfma_f32_16x16x32_bf16 v[94:97], v[152:155], v[200:203], v[94:97]
	v_mfma_f32_16x16x32_bf16 v[90:93], v[160:163], v[200:203], v[90:93]
	v_mfma_f32_16x16x32_bf16 v[78:81], v[152:155], v[208:211], v[78:81]
	v_mfma_f32_16x16x32_bf16 v[74:77], v[160:163], v[208:211], v[74:77]
	v_mfma_f32_16x16x32_bf16 v[118:121], v[164:167], v[180:183], v[118:121]
	v_mfma_f32_16x16x32_bf16 v[114:117], v[172:175], v[180:183], v[114:117]
	v_mfma_f32_16x16x32_bf16 v[102:105], v[164:167], v[188:191], v[102:105]
	v_mfma_f32_16x16x32_bf16 v[98:101], v[172:175], v[188:191], v[98:101]
	v_mfma_f32_16x16x32_bf16 v[86:89], v[164:167], v[196:199], v[86:89]
	v_mfma_f32_16x16x32_bf16 v[82:85], v[172:175], v[196:199], v[82:85]
	v_mfma_f32_16x16x32_bf16 v[70:73], v[164:167], v[204:207], v[70:73]
	v_mfma_f32_16x16x32_bf16 v[66:69], v[172:175], v[204:207], v[66:69]
	v_mfma_f32_16x16x32_bf16 v[118:121], v[168:171], v[184:187], v[118:121]
	v_mfma_f32_16x16x32_bf16 v[114:117], v[176:179], v[184:187], v[114:117]
	v_mfma_f32_16x16x32_bf16 v[102:105], v[168:171], v[192:195], v[102:105]
	v_mfma_f32_16x16x32_bf16 v[98:101], v[176:179], v[192:195], v[98:101]
	v_mfma_f32_16x16x32_bf16 v[86:89], v[168:171], v[200:203], v[86:89]
	v_mfma_f32_16x16x32_bf16 v[82:85], v[176:179], v[200:203], v[82:85]
	v_mfma_f32_16x16x32_bf16 v[70:73], v[168:171], v[208:211], v[70:73]
	v_mfma_f32_16x16x32_bf16 v[66:69], v[176:179], v[208:211], v[66:69]
	s_barrier
	s_mov_b32 m0, s49
	v_lshl_add_u64 v[212:213], v[212:213], 0, s[12:13]
	s_add_u32 s18, s18, 0x40080
	ds_read_b128 v[180:183], v145 offset:49152
	ds_read_b128 v[184:187], v145 offset:50176
	ds_read_b128 v[188:191], v145 offset:51200
	ds_read_b128 v[192:195], v145 offset:52224
	ds_read_b128 v[196:199], v145 offset:53248
	ds_read_b128 v[200:203], v145 offset:54272
	ds_read_b128 v[204:207], v145 offset:55296
	ds_read_b128 v[208:211], v145 offset:56320
	global_load_lds_dwordx4 v[212:213], off
	v_lshl_add_u64 v[212:213], v[214:215], 0, s[12:13]
	s_mov_b32 m0, s50
	s_addc_u32 s19, s19, 0
	global_load_lds_dwordx4 v[212:213], off
	v_lshl_add_u64 v[212:213], s[18:19], 0, v[126:127]
	s_mov_b32 m0, s51
	s_nop 0
	global_load_lds_dwordx4 v[212:213], off
	v_lshl_add_u64 v[212:213], s[18:19], 0, v[122:123]
	s_mov_b32 m0, s52
	s_nop 0
	global_load_lds_dwordx4 v[212:213], off
	v_lshl_add_u64 v[212:213], v[216:217], 0, s[12:13]
	s_mov_b32 m0, s38
	s_nop 0
	global_load_lds_dwordx4 v[212:213], off
	v_lshl_add_u64 v[212:213], v[218:219], 0, s[12:13]
	s_mov_b32 m0, s39
	s_nop 0
	global_load_lds_dwordx4 v[212:213], off
	s_waitcnt vmcnt(8)
	s_waitcnt lgkmcnt(0)
	s_barrier
	s_waitcnt lgkmcnt(0)
	v_mfma_f32_16x16x32_bf16 v[62:65], v[148:151], v[180:183], v[62:65]
	v_mfma_f32_16x16x32_bf16 v[58:61], v[156:159], v[180:183], v[58:61]
	v_mfma_f32_16x16x32_bf16 v[46:49], v[148:151], v[188:191], v[46:49]
	v_mfma_f32_16x16x32_bf16 v[42:45], v[156:159], v[188:191], v[42:45]
	v_mfma_f32_16x16x32_bf16 v[30:33], v[148:151], v[196:199], v[30:33]
	v_mfma_f32_16x16x32_bf16 v[26:29], v[156:159], v[196:199], v[26:29]
	v_mfma_f32_16x16x32_bf16 v[14:17], v[148:151], v[204:207], v[14:17]
	v_mfma_f32_16x16x32_bf16 v[10:13], v[156:159], v[204:207], v[10:13]
	v_mfma_f32_16x16x32_bf16 v[62:65], v[152:155], v[184:187], v[62:65]
	v_mfma_f32_16x16x32_bf16 v[58:61], v[160:163], v[184:187], v[58:61]
	v_mfma_f32_16x16x32_bf16 v[46:49], v[152:155], v[192:195], v[46:49]
	v_mfma_f32_16x16x32_bf16 v[42:45], v[160:163], v[192:195], v[42:45]
	v_mfma_f32_16x16x32_bf16 v[30:33], v[152:155], v[200:203], v[30:33]
	v_mfma_f32_16x16x32_bf16 v[26:29], v[160:163], v[200:203], v[26:29]
	v_mfma_f32_16x16x32_bf16 v[14:17], v[152:155], v[208:211], v[14:17]
	v_mfma_f32_16x16x32_bf16 v[10:13], v[160:163], v[208:211], v[10:13]
	v_mfma_f32_16x16x32_bf16 v[54:57], v[164:167], v[180:183], v[54:57]
	v_mfma_f32_16x16x32_bf16 v[50:53], v[172:175], v[180:183], v[50:53]
	v_mfma_f32_16x16x32_bf16 v[38:41], v[164:167], v[188:191], v[38:41]
	v_mfma_f32_16x16x32_bf16 v[34:37], v[172:175], v[188:191], v[34:37]
	v_mfma_f32_16x16x32_bf16 v[22:25], v[164:167], v[196:199], v[22:25]
	v_mfma_f32_16x16x32_bf16 v[18:21], v[172:175], v[196:199], v[18:21]
	v_mfma_f32_16x16x32_bf16 v[6:9], v[164:167], v[204:207], v[6:9]
	v_mfma_f32_16x16x32_bf16 v[2:5], v[172:175], v[204:207], v[2:5]
	v_mfma_f32_16x16x32_bf16 v[54:57], v[168:171], v[184:187], v[54:57]
	v_mfma_f32_16x16x32_bf16 v[50:53], v[176:179], v[184:187], v[50:53]
	v_mfma_f32_16x16x32_bf16 v[38:41], v[168:171], v[192:195], v[38:41]
	v_mfma_f32_16x16x32_bf16 v[34:37], v[176:179], v[192:195], v[34:37]
	v_mfma_f32_16x16x32_bf16 v[22:25], v[168:171], v[200:203], v[22:25]
	v_mfma_f32_16x16x32_bf16 v[18:21], v[176:179], v[200:203], v[18:21]
	v_mfma_f32_16x16x32_bf16 v[6:9], v[168:171], v[208:211], v[6:9]
	v_mfma_f32_16x16x32_bf16 v[2:5], v[176:179], v[208:211], v[2:5]
	s_barrier
	s_add_i32 s42, s42, 2
	s_add_u32 s16, s16, 0x100
	s_addc_u32 s17, s17, 0
	s_cmp_gt_u32 s42, 13
	s_cbranch_scc0 .LBB0_505
	v_lshl_or_b32 v122, s22, 8, v142
	v_or_b32_e32 v146, s37, v122
	v_lshlrev_b32_e32 v158, 2, v146
	v_mov_b32_e32 v159, 0
	v_lshl_add_u64 v[122:123], s[6:7], 0, v[158:159]
	v_lshl_add_u32 v160, s4, 8, v1
	v_lshlrev_b32_e32 v158, 1, v146
	s_mov_b64 s[8:9], 0x2b03600
	v_lshl_add_u64 v[146:147], s[6:7], 0, v[158:159]
	s_mov_b64 s[4:5], 0xa000000
	v_ashrrev_i32_e32 v161, 31, v160
	v_lshl_add_u64 v[124:125], v[122:123], 0, s[8:9]
	v_add_co_u32_e32 v122, vcc, 0x2b03000, v122
	v_lshl_add_u64 v[162:163], v[146:147], 0, s[4:5]
	v_lshlrev_b64 v[146:147], 11, v[160:161]
	v_addc_co_u32_e32 v123, vcc, 0, v123, vcc
	v_lshl_add_u64 v[146:147], v[162:163], 0, v[146:147]
	v_or_b32_e32 v186, 16, v160
	flat_load_dwordx4 v[138:141], v[124:125] offset:16
	flat_load_dwordx4 v[126:129], v[124:125] offset:512
	flat_load_dwordx4 v[142:145], v[122:123] offset:1536
	s_nop 0
	flat_load_dwordx4 v[122:125], v[124:125] offset:528
	s_nop 0
	global_load_dwordx4 v[166:169], v[146:147], off
	global_load_dwordx4 v[170:173], v[146:147], off offset:256
	v_ashrrev_i32_e32 v187, 31, v186
	v_lshlrev_b64 v[146:147], 11, v[186:187]
	v_lshl_add_u64 v[146:147], v[162:163], 0, v[146:147]
	global_load_dwordx4 v[174:177], v[146:147], off
	global_load_dwordx4 v[178:181], v[146:147], off offset:256
	s_add_u32 s4, s6, 0xe000000
	v_or_b32_e32 v188, 32, v160
	v_or_b32_e32 v164, 48, v160
	s_addc_u32 s5, s7, 0
	v_ashrrev_i32_e32 v189, 31, v188
	v_ashrrev_i32_e32 v165, 31, v164
	v_lshlrev_b64 v[146:147], 12, v[160:161]
	v_lshlrev_b64 v[148:149], 11, v[188:189]
	v_lshlrev_b64 v[150:151], 11, v[164:165]
	v_lshl_add_u64 v[146:147], s[4:5], 0, v[146:147]
	v_lshl_add_u64 v[190:191], v[146:147], 0, v[158:159]
	v_lshl_add_u64 v[146:147], v[162:163], 0, v[148:149]
	v_lshl_add_u64 v[148:149], v[162:163], 0, v[150:151]
	global_load_dwordx4 v[182:185], v[146:147], off
	global_load_dwordx4 v[154:157], v[146:147], off offset:256
	global_load_dwordx4 v[150:153], v[148:149], off
	s_nop 0
	global_load_dwordx4 v[146:149], v[148:149], off offset:256
	s_cmpk_lt_u32 s23, 0x100
	s_waitcnt vmcnt(0) lgkmcnt(0)
	v_pk_add_f32 v[136:137], v[136:137], v[140:141]
	v_pk_add_f32 v[134:135], v[134:135], v[138:139]
	v_pk_add_f32 v[132:133], v[132:133], v[144:145]
	v_pk_add_f32 v[130:131], v[130:131], v[142:143]
	v_pk_add_f32 v[116:117], v[116:117], v[124:125]
	v_pk_add_f32 v[114:115], v[114:115], v[122:123]
	v_lshlrev_b32_e32 v192, 16, v166
	v_and_b32_e32 v193, 0xffff0000, v166
	v_lshlrev_b32_e32 v166, 16, v167
	v_and_b32_e32 v167, 0xffff0000, v167
	v_lshlrev_b32_e32 v194, 16, v168
	v_and_b32_e32 v195, 0xffff0000, v168
	v_lshlrev_b32_e32 v168, 16, v169
	v_and_b32_e32 v169, 0xffff0000, v169
	v_lshlrev_b32_e32 v198, 16, v172
	v_and_b32_e32 v199, 0xffff0000, v172
	v_lshlrev_b32_e32 v172, 16, v173
	v_and_b32_e32 v173, 0xffff0000, v173
	v_pk_add_f32 v[120:121], v[120:121], v[128:129]
	v_pk_add_f32 v[118:119], v[118:119], v[126:127]
	v_lshlrev_b32_e32 v196, 16, v170
	v_and_b32_e32 v197, 0xffff0000, v170
	v_lshlrev_b32_e32 v170, 16, v171
	v_and_b32_e32 v171, 0xffff0000, v171
	v_pk_mul_f32 v[132:133], v[132:133], v[166:167]
	v_pk_mul_f32 v[130:131], v[130:131], v[192:193]
	v_pk_mul_f32 v[136:137], v[136:137], v[168:169]
	v_pk_mul_f32 v[134:135], v[134:135], v[194:195]
	v_pk_mul_f32 v[166:167], v[116:117], v[172:173]
	v_pk_mul_f32 v[168:169], v[114:115], v[198:199]
	v_cvt_pk_bf16_f32 v114, v130, v131
	v_cvt_pk_bf16_f32 v115, v132, v133
	v_cvt_pk_bf16_f32 v116, v134, v135
	v_cvt_pk_bf16_f32 v117, v136, v137
	v_pk_mul_f32 v[120:121], v[120:121], v[170:171]
	v_pk_mul_f32 v[118:119], v[118:119], v[196:197]
	global_store_dwordx4 v[190:191], v[114:117], off offset:2048
	v_pk_add_f32 v[112:113], v[112:113], v[144:145]
	v_pk_add_f32 v[110:111], v[110:111], v[142:143]
	v_cvt_pk_bf16_f32 v114, v118, v119
	v_cvt_pk_bf16_f32 v115, v120, v121
	v_cvt_pk_bf16_f32 v116, v168, v169
	v_cvt_pk_bf16_f32 v117, v166, v167
	global_store_dwordx4 v[190:191], v[114:117], off offset:2304
	v_lshlrev_b32_e32 v118, 16, v175
	v_and_b32_e32 v119, 0xffff0000, v175
	v_lshlrev_b32_e32 v116, 16, v174
	v_and_b32_e32 v117, 0xffff0000, v174
	v_lshlrev_b64 v[114:115], 12, v[186:187]
	v_pk_mul_f32 v[112:113], v[112:113], v[118:119]
	v_pk_mul_f32 v[110:111], v[110:111], v[116:117]
	v_pk_add_f32 v[108:109], v[108:109], v[140:141]
	v_pk_add_f32 v[106:107], v[106:107], v[138:139]
	v_lshlrev_b32_e32 v116, 16, v176
	v_and_b32_e32 v117, 0xffff0000, v176
	v_lshlrev_b32_e32 v118, 16, v177
	v_and_b32_e32 v119, 0xffff0000, v177
	v_pk_mul_f32 v[118:119], v[108:109], v[118:119]
	v_pk_mul_f32 v[108:109], v[106:107], v[116:117]
	v_lshl_add_u64 v[106:107], s[4:5], 0, v[114:115]
	v_lshl_add_u64 v[114:115], v[106:107], 0, v[158:159]
	v_cvt_pk_bf16_f32 v106, v110, v111
	v_cvt_pk_bf16_f32 v107, v112, v113
	v_cvt_pk_bf16_f32 v108, v108, v109
	v_cvt_pk_bf16_f32 v109, v118, v119
	global_store_dwordx4 v[114:115], v[106:109], off offset:2048
	v_pk_add_f32 v[104:105], v[104:105], v[128:129]
	v_pk_add_f32 v[102:103], v[102:103], v[126:127]
	v_lshlrev_b32_e32 v106, 16, v178
	v_and_b32_e32 v107, 0xffff0000, v178
	v_lshlrev_b32_e32 v108, 16, v179
	v_and_b32_e32 v109, 0xffff0000, v179
	v_pk_mul_f32 v[104:105], v[104:105], v[108:109]
	v_pk_mul_f32 v[102:103], v[102:103], v[106:107]
	v_pk_add_f32 v[100:101], v[100:101], v[124:125]
	v_pk_add_f32 v[98:99], v[98:99], v[122:123]
	v_lshlrev_b32_e32 v106, 16, v180
	v_and_b32_e32 v107, 0xffff0000, v180
	v_lshlrev_b32_e32 v108, 16, v181
	v_and_b32_e32 v109, 0xffff0000, v181
	v_pk_mul_f32 v[108:109], v[100:101], v[108:109]
	v_pk_mul_f32 v[100:101], v[98:99], v[106:107]
	v_cvt_pk_bf16_f32 v98, v102, v103
	v_cvt_pk_bf16_f32 v99, v104, v105
	v_pk_add_f32 v[96:97], v[96:97], v[144:145]
	v_cvt_pk_bf16_f32 v100, v100, v101
	v_cvt_pk_bf16_f32 v101, v108, v109
	global_store_dwordx4 v[114:115], v[98:101], off offset:2304
	v_pk_add_f32 v[94:95], v[94:95], v[142:143]
	v_lshlrev_b32_e32 v102, 16, v183
	v_lshlrev_b32_e32 v100, 16, v182
	v_and_b32_e32 v101, 0xffff0000, v182
	v_and_b32_e32 v103, 0xffff0000, v183
	v_lshlrev_b64 v[98:99], 12, v[188:189]
	v_pk_mul_f32 v[96:97], v[96:97], v[102:103]
	v_pk_mul_f32 v[94:95], v[94:95], v[100:101]
	v_pk_add_f32 v[92:93], v[92:93], v[140:141]
	v_pk_add_f32 v[90:91], v[90:91], v[138:139]
	v_lshlrev_b32_e32 v100, 16, v184
	v_and_b32_e32 v101, 0xffff0000, v184
	v_lshlrev_b32_e32 v102, 16, v185
	v_and_b32_e32 v103, 0xffff0000, v185
	v_pk_mul_f32 v[102:103], v[92:93], v[102:103]
	v_pk_mul_f32 v[92:93], v[90:91], v[100:101]
	v_lshl_add_u64 v[90:91], s[4:5], 0, v[98:99]
	v_lshl_add_u64 v[98:99], v[90:91], 0, v[158:159]
	v_cvt_pk_bf16_f32 v90, v94, v95
	v_cvt_pk_bf16_f32 v91, v96, v97
	v_cvt_pk_bf16_f32 v92, v92, v93
	v_cvt_pk_bf16_f32 v93, v102, v103
	global_store_dwordx4 v[98:99], v[90:93], off offset:2048
	v_pk_add_f32 v[88:89], v[88:89], v[128:129]
	v_pk_add_f32 v[86:87], v[86:87], v[126:127]
	v_lshlrev_b32_e32 v90, 16, v154
	v_and_b32_e32 v91, 0xffff0000, v154
	v_lshlrev_b32_e32 v92, 16, v155
	v_and_b32_e32 v93, 0xffff0000, v155
	v_pk_mul_f32 v[88:89], v[88:89], v[92:93]
	v_pk_mul_f32 v[86:87], v[86:87], v[90:91]
	v_pk_add_f32 v[84:85], v[84:85], v[124:125]
	v_pk_add_f32 v[82:83], v[82:83], v[122:123]
	v_lshlrev_b32_e32 v90, 16, v156
	v_and_b32_e32 v91, 0xffff0000, v156
	v_lshlrev_b32_e32 v92, 16, v157
	v_and_b32_e32 v93, 0xffff0000, v157
	v_pk_mul_f32 v[92:93], v[84:85], v[92:93]
	v_pk_mul_f32 v[84:85], v[82:83], v[90:91]
	v_cvt_pk_bf16_f32 v82, v86, v87
	v_cvt_pk_bf16_f32 v83, v88, v89
	v_pk_add_f32 v[80:81], v[80:81], v[144:145]
	v_cvt_pk_bf16_f32 v84, v84, v85
	v_cvt_pk_bf16_f32 v85, v92, v93
	global_store_dwordx4 v[98:99], v[82:85], off offset:2304
	v_pk_add_f32 v[78:79], v[78:79], v[142:143]
	v_lshlrev_b32_e32 v86, 16, v151
	v_lshlrev_b32_e32 v84, 16, v150
	v_and_b32_e32 v85, 0xffff0000, v150
	v_and_b32_e32 v87, 0xffff0000, v151
	v_lshlrev_b64 v[82:83], 12, v[164:165]
	v_pk_mul_f32 v[80:81], v[80:81], v[86:87]
	v_pk_mul_f32 v[78:79], v[78:79], v[84:85]
	v_pk_add_f32 v[76:77], v[76:77], v[140:141]
	v_pk_add_f32 v[74:75], v[74:75], v[138:139]
	v_lshlrev_b32_e32 v84, 16, v152
	v_and_b32_e32 v85, 0xffff0000, v152
	v_lshlrev_b32_e32 v86, 16, v153
	v_and_b32_e32 v87, 0xffff0000, v153
	v_pk_mul_f32 v[86:87], v[76:77], v[86:87]
	v_pk_mul_f32 v[76:77], v[74:75], v[84:85]
	v_lshl_add_u64 v[74:75], s[4:5], 0, v[82:83]
	v_lshl_add_u64 v[84:85], v[74:75], 0, v[158:159]
	v_cvt_pk_bf16_f32 v74, v78, v79
	v_cvt_pk_bf16_f32 v75, v80, v81
	v_cvt_pk_bf16_f32 v76, v76, v77
	v_cvt_pk_bf16_f32 v77, v86, v87
	global_store_dwordx4 v[84:85], v[74:77], off offset:2048
	v_pk_add_f32 v[72:73], v[72:73], v[128:129]
	v_pk_add_f32 v[70:71], v[70:71], v[126:127]
	v_lshlrev_b32_e32 v74, 16, v146
	v_and_b32_e32 v75, 0xffff0000, v146
	v_lshlrev_b32_e32 v76, 16, v147
	v_and_b32_e32 v77, 0xffff0000, v147
	v_add_u32_e32 v100, 0x80, v160
	v_pk_mul_f32 v[72:73], v[72:73], v[76:77]
	v_pk_mul_f32 v[70:71], v[70:71], v[74:75]
	v_pk_add_f32 v[68:69], v[68:69], v[124:125]
	v_pk_add_f32 v[66:67], v[66:67], v[122:123]
	v_lshlrev_b32_e32 v74, 16, v148
	v_and_b32_e32 v75, 0xffff0000, v148
	v_lshlrev_b32_e32 v76, 16, v149
	v_and_b32_e32 v77, 0xffff0000, v149
	v_ashrrev_i32_e32 v101, 31, v100
	v_pk_mul_f32 v[76:77], v[68:69], v[76:77]
	v_pk_mul_f32 v[68:69], v[66:67], v[74:75]
	v_cvt_pk_bf16_f32 v66, v70, v71
	v_lshlrev_b64 v[70:71], 11, v[100:101]
	v_lshl_add_u64 v[70:71], v[162:163], 0, v[70:71]
	v_cvt_pk_bf16_f32 v67, v72, v73
	v_cvt_pk_bf16_f32 v68, v68, v69
	v_cvt_pk_bf16_f32 v69, v76, v77
	global_load_dwordx4 v[80:83], v[70:71], off
	v_add_u32_e32 v102, 0x90, v160
	global_store_dwordx4 v[84:85], v[66:69], off offset:2304
	global_load_dwordx4 v[84:87], v[70:71], off offset:256
	v_ashrrev_i32_e32 v103, 31, v102
	v_lshlrev_b64 v[66:67], 11, v[102:103]
	v_lshl_add_u64 v[66:67], v[162:163], 0, v[66:67]
	global_load_dwordx4 v[88:91], v[66:67], off
	global_load_dwordx4 v[92:95], v[66:67], off offset:256
	v_add_u32_e32 v104, 0xa0, v160
	v_ashrrev_i32_e32 v105, 31, v104
	v_lshlrev_b64 v[66:67], 11, v[104:105]
	v_lshl_add_u64 v[66:67], v[162:163], 0, v[66:67]
	global_load_dwordx4 v[96:99], v[66:67], off
	global_load_dwordx4 v[74:77], v[66:67], off offset:256
	v_add_u32_e32 v78, 0xb0, v160
	v_ashrrev_i32_e32 v79, 31, v78
	v_lshlrev_b64 v[66:67], 11, v[78:79]
	v_lshl_add_u64 v[106:107], v[162:163], 0, v[66:67]
	global_load_dwordx4 v[70:73], v[106:107], off
	global_load_dwordx4 v[66:69], v[106:107], off offset:256
	v_pk_add_f32 v[64:65], v[64:65], v[144:145]
	v_lshlrev_b64 v[100:101], 12, v[100:101]
	v_pk_add_f32 v[60:61], v[60:61], v[140:141]
	v_pk_add_f32 v[58:59], v[58:59], v[138:139]
	v_pk_add_f32 v[62:63], v[62:63], v[142:143]
	v_pk_add_f32 v[56:57], v[56:57], v[128:129]
	v_pk_add_f32 v[54:55], v[54:55], v[126:127]
	v_pk_add_f32 v[52:53], v[52:53], v[124:125]
	v_pk_add_f32 v[50:51], v[50:51], v[122:123]
	v_pk_add_f32 v[48:49], v[48:49], v[144:145]
	v_pk_add_f32 v[46:47], v[46:47], v[142:143]
	v_pk_add_f32 v[44:45], v[44:45], v[140:141]
	v_pk_add_f32 v[42:43], v[42:43], v[138:139]
	v_pk_add_f32 v[40:41], v[40:41], v[128:129]
	v_pk_add_f32 v[38:39], v[38:39], v[126:127]
	v_pk_add_f32 v[36:37], v[36:37], v[124:125]
	v_pk_add_f32 v[34:35], v[34:35], v[122:123]
	v_pk_add_f32 v[32:33], v[32:33], v[144:145]
	v_pk_add_f32 v[30:31], v[30:31], v[142:143]
	v_pk_add_f32 v[28:29], v[28:29], v[140:141]
	v_pk_add_f32 v[26:27], v[26:27], v[138:139]
	v_pk_add_f32 v[24:25], v[24:25], v[128:129]
	v_pk_add_f32 v[22:23], v[22:23], v[126:127]
	v_pk_add_f32 v[20:21], v[20:21], v[124:125]
	v_pk_add_f32 v[18:19], v[18:19], v[122:123]
	v_pk_add_f32 v[16:17], v[16:17], v[144:145]
	v_pk_add_f32 v[14:15], v[14:15], v[142:143]
	v_pk_add_f32 v[12:13], v[12:13], v[140:141]
	v_pk_add_f32 v[10:11], v[10:11], v[138:139]
	v_pk_add_f32 v[8:9], v[8:9], v[128:129]
	v_pk_add_f32 v[6:7], v[6:7], v[126:127]
	v_pk_add_f32 v[4:5], v[4:5], v[124:125]
	v_pk_add_f32 v[2:3], v[2:3], v[122:123]
	s_waitcnt vmcnt(8)
	v_lshlrev_b32_e32 v106, 16, v80
	v_and_b32_e32 v107, 0xffff0000, v80
	v_lshlrev_b32_e32 v80, 16, v81
	v_and_b32_e32 v81, 0xffff0000, v81
	v_pk_mul_f32 v[64:65], v[64:65], v[80:81]
	v_lshlrev_b32_e32 v80, 16, v82
	v_and_b32_e32 v81, 0xffff0000, v82
	v_lshlrev_b32_e32 v82, 16, v83
	v_and_b32_e32 v83, 0xffff0000, v83
	v_pk_mul_f32 v[82:83], v[60:61], v[82:83]
	v_pk_mul_f32 v[60:61], v[58:59], v[80:81]
	v_lshl_add_u64 v[58:59], s[4:5], 0, v[100:101]
	v_pk_mul_f32 v[62:63], v[62:63], v[106:107]
	v_lshl_add_u64 v[80:81], v[58:59], 0, v[158:159]
	v_cvt_pk_bf16_f32 v58, v62, v63
	v_cvt_pk_bf16_f32 v59, v64, v65
	v_cvt_pk_bf16_f32 v60, v60, v61
	v_cvt_pk_bf16_f32 v61, v82, v83
	global_store_dwordx4 v[80:81], v[58:61], off offset:2048
	s_waitcnt vmcnt(7)
	s_nop 0
	v_lshlrev_b32_e32 v58, 16, v84
	v_and_b32_e32 v59, 0xffff0000, v84
	v_lshlrev_b32_e32 v60, 16, v85
	v_and_b32_e32 v61, 0xffff0000, v85
	v_pk_mul_f32 v[56:57], v[56:57], v[60:61]
	v_pk_mul_f32 v[54:55], v[54:55], v[58:59]
	v_lshlrev_b32_e32 v58, 16, v86
	v_and_b32_e32 v59, 0xffff0000, v86
	v_lshlrev_b32_e32 v60, 16, v87
	v_and_b32_e32 v61, 0xffff0000, v87
	v_pk_mul_f32 v[60:61], v[52:53], v[60:61]
	v_pk_mul_f32 v[52:53], v[50:51], v[58:59]
	v_cvt_pk_bf16_f32 v50, v54, v55
	v_cvt_pk_bf16_f32 v51, v56, v57
	s_waitcnt vmcnt(6)
	v_lshlrev_b32_e32 v54, 16, v89
	v_cvt_pk_bf16_f32 v52, v52, v53
	v_cvt_pk_bf16_f32 v53, v60, v61
	global_store_dwordx4 v[80:81], v[50:53], off offset:2304
	v_and_b32_e32 v55, 0xffff0000, v89
	v_pk_mul_f32 v[48:49], v[48:49], v[54:55]
	v_lshlrev_b32_e32 v52, 16, v88
	v_and_b32_e32 v53, 0xffff0000, v88
	v_lshlrev_b64 v[50:51], 12, v[102:103]
	v_pk_mul_f32 v[46:47], v[46:47], v[52:53]
	v_lshlrev_b32_e32 v52, 16, v90
	v_and_b32_e32 v53, 0xffff0000, v90
	v_lshlrev_b32_e32 v54, 16, v91
	v_and_b32_e32 v55, 0xffff0000, v91
	v_pk_mul_f32 v[54:55], v[44:45], v[54:55]
	v_pk_mul_f32 v[44:45], v[42:43], v[52:53]
	v_lshl_add_u64 v[42:43], s[4:5], 0, v[50:51]
	v_lshl_add_u64 v[50:51], v[42:43], 0, v[158:159]
	v_cvt_pk_bf16_f32 v42, v46, v47
	v_cvt_pk_bf16_f32 v43, v48, v49
	v_cvt_pk_bf16_f32 v44, v44, v45
	v_cvt_pk_bf16_f32 v45, v54, v55
	global_store_dwordx4 v[50:51], v[42:45], off offset:2048
	s_waitcnt vmcnt(7)
	s_nop 0
	v_lshlrev_b32_e32 v42, 16, v92
	v_and_b32_e32 v43, 0xffff0000, v92
	v_lshlrev_b32_e32 v44, 16, v93
	v_and_b32_e32 v45, 0xffff0000, v93
	v_pk_mul_f32 v[40:41], v[40:41], v[44:45]
	v_pk_mul_f32 v[38:39], v[38:39], v[42:43]
	v_lshlrev_b32_e32 v42, 16, v94
	v_and_b32_e32 v43, 0xffff0000, v94
	v_lshlrev_b32_e32 v44, 16, v95
	v_and_b32_e32 v45, 0xffff0000, v95
	v_pk_mul_f32 v[44:45], v[36:37], v[44:45]
	v_pk_mul_f32 v[36:37], v[34:35], v[42:43]
	v_cvt_pk_bf16_f32 v34, v38, v39
	v_cvt_pk_bf16_f32 v35, v40, v41
	s_waitcnt vmcnt(6)
	v_lshlrev_b32_e32 v38, 16, v97
	v_cvt_pk_bf16_f32 v36, v36, v37
	v_cvt_pk_bf16_f32 v37, v44, v45
	global_store_dwordx4 v[50:51], v[34:37], off offset:2304
	v_and_b32_e32 v39, 0xffff0000, v97
	v_pk_mul_f32 v[32:33], v[32:33], v[38:39]
	v_lshlrev_b32_e32 v36, 16, v96
	v_and_b32_e32 v37, 0xffff0000, v96
	v_lshlrev_b64 v[34:35], 12, v[104:105]
	v_pk_mul_f32 v[30:31], v[30:31], v[36:37]
	v_lshlrev_b32_e32 v36, 16, v98
	v_and_b32_e32 v37, 0xffff0000, v98
	v_lshlrev_b32_e32 v38, 16, v99
	v_and_b32_e32 v39, 0xffff0000, v99
	v_pk_mul_f32 v[38:39], v[28:29], v[38:39]
	v_pk_mul_f32 v[28:29], v[26:27], v[36:37]
	v_lshl_add_u64 v[26:27], s[4:5], 0, v[34:35]
	v_lshl_add_u64 v[34:35], v[26:27], 0, v[158:159]
	v_cvt_pk_bf16_f32 v26, v30, v31
	v_cvt_pk_bf16_f32 v27, v32, v33
	v_cvt_pk_bf16_f32 v28, v28, v29
	v_cvt_pk_bf16_f32 v29, v38, v39
	global_store_dwordx4 v[34:35], v[26:29], off offset:2048
	s_waitcnt vmcnt(7)
	s_nop 0
	v_lshlrev_b32_e32 v26, 16, v74
	v_and_b32_e32 v27, 0xffff0000, v74
	v_lshlrev_b32_e32 v28, 16, v75
	v_and_b32_e32 v29, 0xffff0000, v75
	v_pk_mul_f32 v[24:25], v[24:25], v[28:29]
	v_pk_mul_f32 v[22:23], v[22:23], v[26:27]
	v_lshlrev_b32_e32 v26, 16, v76
	v_and_b32_e32 v27, 0xffff0000, v76
	v_lshlrev_b32_e32 v28, 16, v77
	v_and_b32_e32 v29, 0xffff0000, v77
	v_pk_mul_f32 v[28:29], v[20:21], v[28:29]
	v_pk_mul_f32 v[20:21], v[18:19], v[26:27]
	v_cvt_pk_bf16_f32 v18, v22, v23
	v_cvt_pk_bf16_f32 v19, v24, v25
	s_waitcnt vmcnt(6)
	v_lshlrev_b32_e32 v22, 16, v71
	v_cvt_pk_bf16_f32 v20, v20, v21
	v_cvt_pk_bf16_f32 v21, v28, v29
	global_store_dwordx4 v[34:35], v[18:21], off offset:2304
	v_and_b32_e32 v23, 0xffff0000, v71
	v_pk_mul_f32 v[16:17], v[16:17], v[22:23]
	v_lshlrev_b32_e32 v20, 16, v70
	v_and_b32_e32 v21, 0xffff0000, v70
	v_lshlrev_b64 v[18:19], 12, v[78:79]
	v_pk_mul_f32 v[14:15], v[14:15], v[20:21]
	v_lshlrev_b32_e32 v20, 16, v72
	v_and_b32_e32 v21, 0xffff0000, v72
	v_lshlrev_b32_e32 v22, 16, v73
	v_and_b32_e32 v23, 0xffff0000, v73
	v_pk_mul_f32 v[22:23], v[12:13], v[22:23]
	v_pk_mul_f32 v[12:13], v[10:11], v[20:21]
	v_lshl_add_u64 v[10:11], s[4:5], 0, v[18:19]
	v_lshl_add_u64 v[18:19], v[10:11], 0, v[158:159]
	v_cvt_pk_bf16_f32 v10, v14, v15
	v_cvt_pk_bf16_f32 v11, v16, v17
	v_cvt_pk_bf16_f32 v12, v12, v13
	v_cvt_pk_bf16_f32 v13, v22, v23
	global_store_dwordx4 v[18:19], v[10:13], off offset:2048
	s_waitcnt vmcnt(7)
	s_nop 0
	v_lshlrev_b32_e32 v10, 16, v66
	v_and_b32_e32 v11, 0xffff0000, v66
	v_lshlrev_b32_e32 v12, 16, v67
	v_and_b32_e32 v13, 0xffff0000, v67
	v_pk_mul_f32 v[8:9], v[8:9], v[12:13]
	v_pk_mul_f32 v[6:7], v[6:7], v[10:11]
	v_lshlrev_b32_e32 v10, 16, v68
	v_and_b32_e32 v11, 0xffff0000, v68
	v_lshlrev_b32_e32 v12, 16, v69
	v_and_b32_e32 v13, 0xffff0000, v69
	v_pk_mul_f32 v[12:13], v[4:5], v[12:13]
	v_pk_mul_f32 v[4:5], v[2:3], v[10:11]
	v_cvt_pk_bf16_f32 v2, v6, v7
	v_cvt_pk_bf16_f32 v3, v8, v9
	s_nop 0
	v_cvt_pk_bf16_f32 v4, v4, v5
	v_cvt_pk_bf16_f32 v5, v12, v13
	global_store_dwordx4 v[18:19], v[2:5], off offset:2304
	s_waitcnt vmcnt(0)
	s_cbranch_scc0 .LBB0_508
	s_barrier

.LBB0_630:
	v_add_u32_e32 v153, s50, v151
	ds_read_b128 v[154:157], v153
	ds_read_b128 v[158:161], v153 offset:1024
	ds_read_b128 v[162:165], v153 offset:2048
	ds_read_b128 v[166:169], v153 offset:3072
	v_add_u32_e32 v153, s51, v151
	s_add_u32 s30, s12, s28
	ds_read_b128 v[170:173], v153
	ds_read_b128 v[174:177], v153 offset:1024
	ds_read_b128 v[178:181], v153 offset:2048
	ds_read_b128 v[182:185], v153 offset:3072
	s_addc_u32 s31, s13, s29
	s_add_u32 s30, s30, 0x100
	s_addc_u32 s31, s31, 0
	s_add_u32 s58, s53, s28
	s_addc_u32 s59, s54, s29
	s_cmpk_eq_i32 s28, 0xf00
	s_cselect_b32 s35, s21, s31
	s_cselect_b32 s34, s55, s30
	s_cselect_b32 s31, s19, s59
	s_cselect_b32 s30, s56, s58
	v_lshl_add_u64 v[202:203], v[148:149], 0, s[28:29]
	s_add_i32 m0, s43, 0xc000
	ds_read_b128 v[186:189], v152
	ds_read_b128 v[190:193], v152 offset:1024
	ds_read_b128 v[194:197], v152 offset:2048
	ds_read_b128 v[198:201], v152 offset:3072
	ds_read_b128 v[206:209], v152 offset:4096
	ds_read_b128 v[210:213], v152 offset:5120
	ds_read_b128 v[214:217], v152 offset:6144
	ds_read_b128 v[218:221], v152 offset:7168
	global_load_lds_dwordx4 v[202:203], off
	v_lshl_add_u64 v[202:203], v[146:147], 0, s[28:29]
	s_add_i32 m0, s43, 0xe000
	s_nop 0
	global_load_lds_dwordx4 v[202:203], off
	s_waitcnt vmcnt(8)
	s_waitcnt lgkmcnt(0)
	s_barrier
	s_waitcnt lgkmcnt(0)
	v_mfma_f32_16x16x32_bf16 v[126:129], v[154:157], v[186:189], v[126:129]
	v_mfma_f32_16x16x32_bf16 v[122:125], v[162:165], v[186:189], v[122:125]
	v_mfma_f32_16x16x32_bf16 v[110:113], v[154:157], v[194:197], v[110:113]
	v_mfma_f32_16x16x32_bf16 v[106:109], v[162:165], v[194:197], v[106:109]
	v_mfma_f32_16x16x32_bf16 v[94:97], v[154:157], v[206:209], v[94:97]
	v_mfma_f32_16x16x32_bf16 v[90:93], v[162:165], v[206:209], v[90:93]
	v_mfma_f32_16x16x32_bf16 v[82:85], v[154:157], v[214:217], v[82:85]
	v_mfma_f32_16x16x32_bf16 v[74:77], v[162:165], v[214:217], v[74:77]
	v_mfma_f32_16x16x32_bf16 v[126:129], v[158:161], v[190:193], v[126:129]
	v_mfma_f32_16x16x32_bf16 v[122:125], v[166:169], v[190:193], v[122:125]
	v_mfma_f32_16x16x32_bf16 v[110:113], v[158:161], v[198:201], v[110:113]
	v_mfma_f32_16x16x32_bf16 v[106:109], v[166:169], v[198:201], v[106:109]
	v_mfma_f32_16x16x32_bf16 v[94:97], v[158:161], v[210:213], v[94:97]
	v_mfma_f32_16x16x32_bf16 v[90:93], v[166:169], v[210:213], v[90:93]
	v_mfma_f32_16x16x32_bf16 v[82:85], v[158:161], v[218:221], v[82:85]
	v_mfma_f32_16x16x32_bf16 v[74:77], v[166:169], v[218:221], v[74:77]
	v_mfma_f32_16x16x32_bf16 v[118:121], v[170:173], v[186:189], v[118:121]
	v_mfma_f32_16x16x32_bf16 v[114:117], v[178:181], v[186:189], v[114:117]
	v_mfma_f32_16x16x32_bf16 v[102:105], v[170:173], v[194:197], v[102:105]
	v_mfma_f32_16x16x32_bf16 v[98:101], v[178:181], v[194:197], v[98:101]
	v_mfma_f32_16x16x32_bf16 v[86:89], v[170:173], v[206:209], v[86:89]
	v_mfma_f32_16x16x32_bf16 v[78:81], v[178:181], v[206:209], v[78:81]
	v_mfma_f32_16x16x32_bf16 v[70:73], v[170:173], v[214:217], v[70:73]
	v_mfma_f32_16x16x32_bf16 v[66:69], v[178:181], v[214:217], v[66:69]
	v_mfma_f32_16x16x32_bf16 v[118:121], v[174:177], v[190:193], v[118:121]
	v_mfma_f32_16x16x32_bf16 v[114:117], v[182:185], v[190:193], v[114:117]
	v_mfma_f32_16x16x32_bf16 v[102:105], v[174:177], v[198:201], v[102:105]
	v_mfma_f32_16x16x32_bf16 v[98:101], v[182:185], v[198:201], v[98:101]
	v_mfma_f32_16x16x32_bf16 v[86:89], v[174:177], v[210:213], v[86:89]
	v_mfma_f32_16x16x32_bf16 v[78:81], v[182:185], v[210:213], v[78:81]
	v_mfma_f32_16x16x32_bf16 v[70:73], v[174:177], v[218:221], v[70:73]
	v_mfma_f32_16x16x32_bf16 v[66:69], v[182:185], v[218:221], v[66:69]
	s_barrier
	s_add_i32 s58, s50, s41
	v_lshl_add_u64 v[202:203], s[30:31], 0, v[132:133]
	s_mov_b32 m0, s58
	ds_read_b128 v[186:189], v152 offset:16384
	ds_read_b128 v[190:193], v152 offset:17408
	ds_read_b128 v[194:197], v152 offset:18432
	ds_read_b128 v[198:201], v152 offset:19456
	ds_read_b128 v[206:209], v152 offset:20480
	ds_read_b128 v[210:213], v152 offset:21504
	ds_read_b128 v[214:217], v152 offset:22528
	ds_read_b128 v[218:221], v152 offset:23552
	global_load_lds_dwordx4 v[202:203], off
	s_add_i32 m0, s58, 0x2000
	s_add_u32 s58, s30, 0x80000
	v_lshl_add_u64 v[222:223], s[30:31], 0, v[136:137]
	s_addc_u32 s59, s31, 0
	s_add_i32 s60, s51, s41
	global_load_lds_dwordx4 v[222:223], off
	v_lshl_add_u64 v[224:225], s[58:59], 0, v[132:133]
	s_mov_b32 m0, s60
	v_lshl_add_u64 v[226:227], s[34:35], 0, v[134:135]
	global_load_lds_dwordx4 v[224:225], off
	v_lshl_add_u64 v[224:225], s[58:59], 0, v[136:137]
	s_add_i32 m0, s60, 0x2000
	s_nop 0
	global_load_lds_dwordx4 v[224:225], off
	v_lshl_add_u64 v[224:225], s[34:35], 0, v[130:131]
	s_mov_b32 m0, s43
	s_nop 0
	global_load_lds_dwordx4 v[224:225], off
	s_mov_b32 m0, s44
	s_nop 0
	global_load_lds_dwordx4 v[226:227], off
	s_waitcnt vmcnt(8)
	s_waitcnt lgkmcnt(0)
	s_barrier
	s_waitcnt lgkmcnt(0)
	v_mfma_f32_16x16x32_bf16 v[62:65], v[154:157], v[186:189], v[62:65]
	v_mfma_f32_16x16x32_bf16 v[58:61], v[162:165], v[186:189], v[58:61]
	v_mfma_f32_16x16x32_bf16 v[46:49], v[154:157], v[194:197], v[46:49]
	v_mfma_f32_16x16x32_bf16 v[42:45], v[162:165], v[194:197], v[42:45]
	v_mfma_f32_16x16x32_bf16 v[30:33], v[154:157], v[206:209], v[30:33]
	v_mfma_f32_16x16x32_bf16 v[26:29], v[162:165], v[206:209], v[26:29]
	v_mfma_f32_16x16x32_bf16 v[18:21], v[154:157], v[214:217], v[18:21]
	v_mfma_f32_16x16x32_bf16 v[10:13], v[162:165], v[214:217], v[10:13]
	v_mfma_f32_16x16x32_bf16 v[62:65], v[158:161], v[190:193], v[62:65]
	v_mfma_f32_16x16x32_bf16 v[58:61], v[166:169], v[190:193], v[58:61]
	v_mfma_f32_16x16x32_bf16 v[46:49], v[158:161], v[198:201], v[46:49]
	v_mfma_f32_16x16x32_bf16 v[42:45], v[166:169], v[198:201], v[42:45]
	v_mfma_f32_16x16x32_bf16 v[30:33], v[158:161], v[210:213], v[30:33]
	v_mfma_f32_16x16x32_bf16 v[26:29], v[166:169], v[210:213], v[26:29]
	v_mfma_f32_16x16x32_bf16 v[18:21], v[158:161], v[218:221], v[18:21]
	v_mfma_f32_16x16x32_bf16 v[10:13], v[166:169], v[218:221], v[10:13]
	v_mfma_f32_16x16x32_bf16 v[54:57], v[170:173], v[186:189], v[54:57]
	v_mfma_f32_16x16x32_bf16 v[50:53], v[178:181], v[186:189], v[50:53]
	v_mfma_f32_16x16x32_bf16 v[38:41], v[170:173], v[194:197], v[38:41]
	v_mfma_f32_16x16x32_bf16 v[34:37], v[178:181], v[194:197], v[34:37]
	v_mfma_f32_16x16x32_bf16 v[22:25], v[170:173], v[206:209], v[22:25]
	v_mfma_f32_16x16x32_bf16 v[14:17], v[178:181], v[206:209], v[14:17]
	v_mfma_f32_16x16x32_bf16 v[6:9], v[170:173], v[214:217], v[6:9]
	v_mfma_f32_16x16x32_bf16 v[2:5], v[178:181], v[214:217], v[2:5]
	v_mfma_f32_16x16x32_bf16 v[54:57], v[174:177], v[190:193], v[54:57]
	v_mfma_f32_16x16x32_bf16 v[50:53], v[182:185], v[190:193], v[50:53]
	v_mfma_f32_16x16x32_bf16 v[38:41], v[174:177], v[198:201], v[38:41]
	v_mfma_f32_16x16x32_bf16 v[34:37], v[182:185], v[198:201], v[34:37]
	v_mfma_f32_16x16x32_bf16 v[22:25], v[174:177], v[210:213], v[22:25]
	v_mfma_f32_16x16x32_bf16 v[14:17], v[182:185], v[210:213], v[14:17]
	v_mfma_f32_16x16x32_bf16 v[6:9], v[174:177], v[218:221], v[6:9]
	v_mfma_f32_16x16x32_bf16 v[2:5], v[182:185], v[218:221], v[2:5]
	s_barrier
	s_add_i32 s58, 0, 0x18000
	v_add_u32_e32 v153, s58, v151
	s_add_i32 s59, 0, 0x1c000
	ds_read_b128 v[154:157], v153
	ds_read_b128 v[158:161], v153 offset:1024
	ds_read_b128 v[162:165], v153 offset:2048
	ds_read_b128 v[166:169], v153 offset:3072
	v_add_u32_e32 v153, s59, v151
	ds_read_b128 v[170:173], v153
	ds_read_b128 v[174:177], v153 offset:1024
	ds_read_b128 v[178:181], v153 offset:2048
	ds_read_b128 v[182:185], v153 offset:3072
	s_add_u32 s34, s34, 0x80000
	s_addc_u32 s35, s35, 0
	s_mov_b32 m0, s45
	v_lshl_add_u64 v[228:229], s[34:35], 0, v[130:131]
	ds_read_b128 v[186:189], v152 offset:32768
	ds_read_b128 v[190:193], v152 offset:33792
	ds_read_b128 v[194:197], v152 offset:34816
	ds_read_b128 v[198:201], v152 offset:35840
	ds_read_b128 v[206:209], v152 offset:36864
	ds_read_b128 v[210:213], v152 offset:37888
	ds_read_b128 v[214:217], v152 offset:38912
	ds_read_b128 v[218:221], v152 offset:39936
	global_load_lds_dwordx4 v[228:229], off
	v_lshl_add_u64 v[228:229], s[34:35], 0, v[134:135]
	s_mov_b32 m0, s46
	s_nop 0
	global_load_lds_dwordx4 v[228:229], off
	s_waitcnt vmcnt(8)
	s_waitcnt lgkmcnt(0)
	s_barrier
	s_waitcnt lgkmcnt(0)
	v_mfma_f32_16x16x32_bf16 v[126:129], v[154:157], v[186:189], v[126:129]
	v_mfma_f32_16x16x32_bf16 v[122:125], v[162:165], v[186:189], v[122:125]
	v_mfma_f32_16x16x32_bf16 v[110:113], v[154:157], v[194:197], v[110:113]
	v_mfma_f32_16x16x32_bf16 v[106:109], v[162:165], v[194:197], v[106:109]
	v_mfma_f32_16x16x32_bf16 v[94:97], v[154:157], v[206:209], v[94:97]
	v_mfma_f32_16x16x32_bf16 v[90:93], v[162:165], v[206:209], v[90:93]
	v_mfma_f32_16x16x32_bf16 v[82:85], v[154:157], v[214:217], v[82:85]
	v_mfma_f32_16x16x32_bf16 v[74:77], v[162:165], v[214:217], v[74:77]
	v_mfma_f32_16x16x32_bf16 v[126:129], v[158:161], v[190:193], v[126:129]
	v_mfma_f32_16x16x32_bf16 v[122:125], v[166:169], v[190:193], v[122:125]
	v_mfma_f32_16x16x32_bf16 v[110:113], v[158:161], v[198:201], v[110:113]
	v_mfma_f32_16x16x32_bf16 v[106:109], v[166:169], v[198:201], v[106:109]
	v_mfma_f32_16x16x32_bf16 v[94:97], v[158:161], v[210:213], v[94:97]
	v_mfma_f32_16x16x32_bf16 v[90:93], v[166:169], v[210:213], v[90:93]
	v_mfma_f32_16x16x32_bf16 v[82:85], v[158:161], v[218:221], v[82:85]
	v_mfma_f32_16x16x32_bf16 v[74:77], v[166:169], v[218:221], v[74:77]
	v_mfma_f32_16x16x32_bf16 v[118:121], v[170:173], v[186:189], v[118:121]
	v_mfma_f32_16x16x32_bf16 v[114:117], v[178:181], v[186:189], v[114:117]
	v_mfma_f32_16x16x32_bf16 v[102:105], v[170:173], v[194:197], v[102:105]
	v_mfma_f32_16x16x32_bf16 v[98:101], v[178:181], v[194:197], v[98:101]
	v_mfma_f32_16x16x32_bf16 v[86:89], v[170:173], v[206:209], v[86:89]
	v_mfma_f32_16x16x32_bf16 v[78:81], v[178:181], v[206:209], v[78:81]
	v_mfma_f32_16x16x32_bf16 v[70:73], v[170:173], v[214:217], v[70:73]
	v_mfma_f32_16x16x32_bf16 v[66:69], v[178:181], v[214:217], v[66:69]
	v_mfma_f32_16x16x32_bf16 v[118:121], v[174:177], v[190:193], v[118:121]
	v_mfma_f32_16x16x32_bf16 v[114:117], v[182:185], v[190:193], v[114:117]
	v_mfma_f32_16x16x32_bf16 v[102:105], v[174:177], v[198:201], v[102:105]
	v_mfma_f32_16x16x32_bf16 v[98:101], v[182:185], v[198:201], v[98:101]
	v_mfma_f32_16x16x32_bf16 v[86:89], v[174:177], v[210:213], v[86:89]
	v_mfma_f32_16x16x32_bf16 v[78:81], v[182:185], v[210:213], v[78:81]
	v_mfma_f32_16x16x32_bf16 v[70:73], v[174:177], v[218:221], v[70:73]
	v_mfma_f32_16x16x32_bf16 v[66:69], v[182:185], v[218:221], v[66:69]
	s_barrier
	s_add_i32 s34, s58, s41
	v_lshl_add_u64 v[202:203], v[202:203], 0, s[16:17]
	s_mov_b32 m0, s34
	ds_read_b128 v[186:189], v152 offset:49152
	ds_read_b128 v[190:193], v152 offset:50176
	ds_read_b128 v[194:197], v152 offset:51200
	ds_read_b128 v[198:201], v152 offset:52224
	ds_read_b128 v[206:209], v152 offset:53248
	ds_read_b128 v[210:213], v152 offset:54272
	ds_read_b128 v[214:217], v152 offset:55296
	ds_read_b128 v[218:221], v152 offset:56320
	global_load_lds_dwordx4 v[202:203], off
	s_add_i32 m0, s34, 0x2000
	s_add_u32 s30, s30, 0x80080
	v_lshl_add_u64 v[202:203], v[222:223], 0, s[16:17]
	s_addc_u32 s31, s31, 0
	s_add_i32 s34, s59, s41
	global_load_lds_dwordx4 v[202:203], off
	v_lshl_add_u64 v[202:203], s[30:31], 0, v[132:133]
	s_mov_b32 m0, s34
	s_nop 0
	global_load_lds_dwordx4 v[202:203], off
	v_lshl_add_u64 v[202:203], s[30:31], 0, v[136:137]
	s_add_i32 m0, s34, 0x2000
	s_nop 0
	global_load_lds_dwordx4 v[202:203], off
	v_lshl_add_u64 v[202:203], v[224:225], 0, s[16:17]
	s_mov_b32 m0, s47
	s_nop 0
	global_load_lds_dwordx4 v[202:203], off
	v_lshl_add_u64 v[202:203], v[226:227], 0, s[16:17]
	s_mov_b32 m0, s48
	s_nop 0
	global_load_lds_dwordx4 v[202:203], off
	s_waitcnt vmcnt(8)
	s_waitcnt lgkmcnt(0)
	s_barrier
	s_waitcnt lgkmcnt(0)
	v_mfma_f32_16x16x32_bf16 v[62:65], v[154:157], v[186:189], v[62:65]
	v_mfma_f32_16x16x32_bf16 v[58:61], v[162:165], v[186:189], v[58:61]
	v_mfma_f32_16x16x32_bf16 v[46:49], v[154:157], v[194:197], v[46:49]
	v_mfma_f32_16x16x32_bf16 v[42:45], v[162:165], v[194:197], v[42:45]
	v_mfma_f32_16x16x32_bf16 v[30:33], v[154:157], v[206:209], v[30:33]
	v_mfma_f32_16x16x32_bf16 v[26:29], v[162:165], v[206:209], v[26:29]
	v_mfma_f32_16x16x32_bf16 v[18:21], v[154:157], v[214:217], v[18:21]
	v_mfma_f32_16x16x32_bf16 v[10:13], v[162:165], v[214:217], v[10:13]
	v_mfma_f32_16x16x32_bf16 v[62:65], v[158:161], v[190:193], v[62:65]
	v_mfma_f32_16x16x32_bf16 v[58:61], v[166:169], v[190:193], v[58:61]
	v_mfma_f32_16x16x32_bf16 v[46:49], v[158:161], v[198:201], v[46:49]
	v_mfma_f32_16x16x32_bf16 v[42:45], v[166:169], v[198:201], v[42:45]
	v_mfma_f32_16x16x32_bf16 v[30:33], v[158:161], v[210:213], v[30:33]
	v_mfma_f32_16x16x32_bf16 v[26:29], v[166:169], v[210:213], v[26:29]
	v_mfma_f32_16x16x32_bf16 v[18:21], v[158:161], v[218:221], v[18:21]
	v_mfma_f32_16x16x32_bf16 v[10:13], v[166:169], v[218:221], v[10:13]
	v_mfma_f32_16x16x32_bf16 v[54:57], v[170:173], v[186:189], v[54:57]
	v_mfma_f32_16x16x32_bf16 v[50:53], v[178:181], v[186:189], v[50:53]
	v_mfma_f32_16x16x32_bf16 v[38:41], v[170:173], v[194:197], v[38:41]
	v_mfma_f32_16x16x32_bf16 v[34:37], v[178:181], v[194:197], v[34:37]
	v_mfma_f32_16x16x32_bf16 v[22:25], v[170:173], v[206:209], v[22:25]
	v_mfma_f32_16x16x32_bf16 v[14:17], v[178:181], v[206:209], v[14:17]
	v_mfma_f32_16x16x32_bf16 v[6:9], v[170:173], v[214:217], v[6:9]
	v_mfma_f32_16x16x32_bf16 v[2:5], v[178:181], v[214:217], v[2:5]
	v_mfma_f32_16x16x32_bf16 v[54:57], v[174:177], v[190:193], v[54:57]
	v_mfma_f32_16x16x32_bf16 v[50:53], v[182:185], v[190:193], v[50:53]
	v_mfma_f32_16x16x32_bf16 v[38:41], v[174:177], v[198:201], v[38:41]
	v_mfma_f32_16x16x32_bf16 v[34:37], v[182:185], v[198:201], v[34:37]
	v_mfma_f32_16x16x32_bf16 v[22:25], v[174:177], v[210:213], v[22:25]
	v_mfma_f32_16x16x32_bf16 v[14:17], v[182:185], v[210:213], v[14:17]
	v_mfma_f32_16x16x32_bf16 v[6:9], v[174:177], v[218:221], v[6:9]
	v_mfma_f32_16x16x32_bf16 v[2:5], v[182:185], v[218:221], v[2:5]
	s_barrier
	s_add_i32 s57, s57, 2
	s_add_u32 s28, s28, 0x100
	s_addc_u32 s29, s29, 0
	s_cmp_gt_u32 s57, 29
	s_cbranch_scc0 .LBB0_630
	s_add_u32 s28, s53, 0xffffff00
	s_addc_u32 s29, s54, -1
	s_andn2_b64 vcc, exec, s[4:5]
	s_cbranch_vccnz .LBB0_621
	v_mov_b32_e32 v2, 0
	s_mov_b32 s10, s18
	s_mov_b32 s8, s20
	s_mov_b64 s[12:13], s[26:27]
	s_mov_b32 s49, s52
	v_mov_b32_e32 v3, v2
	v_mov_b32_e32 v4, v2
	v_mov_b32_e32 v5, v2
	v_mov_b32_e32 v6, v2
	v_mov_b32_e32 v7, v2
	v_mov_b32_e32 v8, v2
	v_mov_b32_e32 v9, v2
	v_mov_b32_e32 v14, v2
	v_mov_b32_e32 v15, v2
	v_mov_b32_e32 v16, v2
	v_mov_b32_e32 v17, v2
	v_mov_b32_e32 v22, v2
	v_mov_b32_e32 v23, v2
	v_mov_b32_e32 v24, v2
	v_mov_b32_e32 v25, v2
	v_mov_b32_e32 v34, v2
	v_mov_b32_e32 v35, v2
	v_mov_b32_e32 v36, v2
	v_mov_b32_e32 v37, v2
	v_mov_b32_e32 v38, v2
	v_mov_b32_e32 v39, v2
	v_mov_b32_e32 v40, v2
	v_mov_b32_e32 v41, v2
	v_mov_b32_e32 v50, v2
	v_mov_b32_e32 v51, v2
	v_mov_b32_e32 v52, v2
	v_mov_b32_e32 v53, v2
	v_mov_b32_e32 v54, v2
	v_mov_b32_e32 v55, v2
	v_mov_b32_e32 v56, v2
	v_mov_b32_e32 v57, v2
	v_mov_b32_e32 v10, v2
	v_mov_b32_e32 v11, v2
	v_mov_b32_e32 v12, v2
	v_mov_b32_e32 v13, v2
	v_mov_b32_e32 v18, v2
	v_mov_b32_e32 v19, v2
	v_mov_b32_e32 v20, v2
	v_mov_b32_e32 v21, v2
	v_mov_b32_e32 v26, v2
	v_mov_b32_e32 v27, v2
	v_mov_b32_e32 v28, v2
	v_mov_b32_e32 v29, v2
	v_mov_b32_e32 v30, v2
	v_mov_b32_e32 v31, v2
	v_mov_b32_e32 v32, v2
	v_mov_b32_e32 v33, v2
	v_mov_b32_e32 v42, v2
	v_mov_b32_e32 v43, v2
	v_mov_b32_e32 v44, v2
	v_mov_b32_e32 v45, v2
	v_mov_b32_e32 v46, v2
	v_mov_b32_e32 v47, v2
	v_mov_b32_e32 v48, v2
	v_mov_b32_e32 v49, v2
	v_mov_b32_e32 v58, v2
	v_mov_b32_e32 v59, v2
	v_mov_b32_e32 v60, v2
	v_mov_b32_e32 v61, v2
	v_mov_b32_e32 v62, v2
	v_mov_b32_e32 v63, v2
	v_mov_b32_e32 v64, v2
	v_mov_b32_e32 v65, v2
	v_mov_b32_e32 v66, v2
	v_mov_b32_e32 v67, v2
	v_mov_b32_e32 v68, v2
	v_mov_b32_e32 v69, v2
	v_mov_b32_e32 v70, v2
	v_mov_b32_e32 v71, v2
	v_mov_b32_e32 v72, v2
	v_mov_b32_e32 v73, v2
	v_mov_b32_e32 v78, v2
	v_mov_b32_e32 v79, v2
	v_mov_b32_e32 v80, v2
	v_mov_b32_e32 v81, v2
	v_mov_b32_e32 v86, v2
	v_mov_b32_e32 v87, v2
	v_mov_b32_e32 v88, v2
	v_mov_b32_e32 v89, v2
	v_mov_b32_e32 v98, v2
	v_mov_b32_e32 v99, v2
	v_mov_b32_e32 v100, v2
	v_mov_b32_e32 v101, v2
	v_mov_b32_e32 v102, v2
	v_mov_b32_e32 v103, v2
	v_mov_b32_e32 v104, v2
	v_mov_b32_e32 v105, v2
	v_mov_b32_e32 v114, v2
	v_mov_b32_e32 v115, v2
	v_mov_b32_e32 v116, v2
	v_mov_b32_e32 v117, v2
	v_mov_b32_e32 v118, v2
	v_mov_b32_e32 v119, v2
	v_mov_b32_e32 v120, v2
	v_mov_b32_e32 v121, v2
	v_mov_b32_e32 v74, v2
	v_mov_b32_e32 v75, v2
	v_mov_b32_e32 v76, v2
	v_mov_b32_e32 v77, v2
	v_mov_b32_e32 v82, v2
	v_mov_b32_e32 v83, v2
	v_mov_b32_e32 v84, v2
	v_mov_b32_e32 v85, v2
	v_mov_b32_e32 v90, v2
	v_mov_b32_e32 v91, v2
	v_mov_b32_e32 v92, v2
	v_mov_b32_e32 v93, v2
	v_mov_b32_e32 v94, v2
	v_mov_b32_e32 v95, v2
	v_mov_b32_e32 v96, v2
	v_mov_b32_e32 v97, v2
	v_mov_b32_e32 v106, v2
	v_mov_b32_e32 v107, v2
	v_mov_b32_e32 v108, v2
	v_mov_b32_e32 v109, v2
	v_mov_b32_e32 v110, v2
	v_mov_b32_e32 v111, v2
	v_mov_b32_e32 v112, v2
	v_mov_b32_e32 v113, v2
	v_mov_b32_e32 v122, v2
	v_mov_b32_e32 v123, v2
	v_mov_b32_e32 v124, v2
	v_mov_b32_e32 v125, v2
	v_mov_b32_e32 v126, v2
	v_mov_b32_e32 v127, v2
	v_mov_b32_e32 v128, v2
	v_mov_b32_e32 v129, v2
	s_andn2_b64 vcc, exec, s[0:1]
	s_cbranch_vccnz .LBB0_622
